# stack: pool loads hoisted to one batch + pipelined x->bf16 prologue + sg u-load hoist + conv pipelined loads + sg part1 batching + reversed N=1024 order + trimmed K-loop DMA
# speedup vs baseline: 1.0120x; 1.0040x over previous
; __device__ __forceinline__ void pool_item(int l, int it, LAS unsigned char* lds, const bf16_t* PLB, bf16_t* YC, const float* pool_w, const float* pool_scale, int tid, int lane, int wave) {
;     ...
;         for (int ib = 0; ib < 48; ib += 12) {
;             unsigned raw[12]; const void* pp[12];
; #pragma unroll
;             for (int j = 0; j < 12; ++j) { const int off = ts - 15 + (ib + j < 47 ? ib + j : 46); pp[j] = PLB + (r0 + (pos0 + off >= 0 ? off : -pos0)) * BW; }
;             ld_u16_s12(raw, (unsigned)c * 2u, pp);
.LBB0_87:
	s_and_b32 s72, s3, 0xfc0
	v_writelane_b32 v254, s2, 22
	s_sub_i32 s4, 0, s72
	v_writelane_b32 v254, s3, 24
	s_ashr_i32 s5, s4, 31
	v_readlane_b32 s2, v253, 46
	v_mov_b64_e32 v[0:1], s[4:5]
	v_readlane_b32 s3, v253, 47
	v_mov_b64_e32 v[2:3], s[42:43]
	s_mov_b64 s[70:71], s[42:43]
	v_cmp_gt_i64_e32 vcc, s[2:3], v[0:1]
	s_and_b64 s[0:1], vcc, exec
	s_cselect_b32 s0, s3, s5
	s_cselect_b32 s1, s2, s4
	v_readlane_b32 s2, v253, 50
	s_add_u32 s30, s1, s20
	v_readlane_b32 s3, v253, 51
	s_addc_u32 s31, s0, s21
	v_readlane_b32 s16, v255, 46
	v_cmp_gt_i64_e32 vcc, s[2:3], v[0:1]
	s_and_b64 s[0:1], vcc, exec
	s_cselect_b32 s0, s3, s5
	s_cselect_b32 s1, s2, s4
	v_readlane_b32 s2, v253, 52
	s_add_u32 s22, s1, s20
	v_readlane_b32 s3, v253, 53
	s_addc_u32 s23, s0, s21
	v_readlane_b32 s17, v255, 47
	v_cmp_gt_i64_e32 vcc, s[2:3], v[0:1]
	s_and_b64 s[0:1], vcc, exec
	s_cselect_b32 s0, s3, s5
	s_cselect_b32 s1, s2, s4
	v_readlane_b32 s2, v253, 54
	s_add_u32 s24, s1, s20
	v_readlane_b32 s3, v253, 55
	s_addc_u32 s25, s0, s21
	v_readlane_b32 s18, v255, 52
	v_cmp_gt_i64_e32 vcc, s[2:3], v[0:1]
	s_and_b64 s[0:1], vcc, exec
	s_cselect_b32 s0, s3, s5
	s_cselect_b32 s1, s2, s4
	v_readlane_b32 s2, v253, 56
	s_add_u32 s58, s1, s20
	v_readlane_b32 s3, v253, 57
	s_addc_u32 s59, s0, s21
	v_readlane_b32 s19, v255, 53
	v_cmp_gt_i64_e32 vcc, s[2:3], v[0:1]
	s_and_b64 s[0:1], vcc, exec
	s_cselect_b32 s0, s3, s5
	s_cselect_b32 s1, s2, s4
	v_readlane_b32 s2, v253, 58
	s_add_u32 s64, s1, s20
	v_readlane_b32 s3, v253, 59
	s_addc_u32 s65, s0, s21
	v_readlane_b32 s68, v255, 56
	v_cmp_gt_i64_e32 vcc, s[2:3], v[0:1]
	s_and_b64 s[0:1], vcc, exec
	s_cselect_b32 s0, s3, s5
	s_cselect_b32 s1, s2, s4
	v_readlane_b32 s2, v254, 17
	s_add_u32 s60, s1, s20
	v_readlane_b32 s3, v254, 18
	s_addc_u32 s61, s0, s21
	v_readlane_b32 s69, v255, 57
	v_cmp_gt_i64_e32 vcc, s[2:3], v[0:1]
	s_and_b64 s[0:1], vcc, exec
	s_cselect_b32 s1, s2, s4
	s_cselect_b32 s0, s3, s5
	s_add_u32 s1, s1, s20
	v_writelane_b32 v254, s1, 25
	s_addc_u32 s0, s0, s21
	v_writelane_b32 v254, s0, 26
	s_nop 0
	v_readlane_b32 s2, v254, 14
	v_readlane_b32 s3, v254, 15
	s_nop 1
	v_cmp_gt_i64_e32 vcc, s[2:3], v[0:1]
	s_and_b64 s[0:1], vcc, exec
	s_cselect_b32 s1, s2, s4
	s_cselect_b32 s0, s3, s5
	s_add_u32 s1, s1, s20
	v_writelane_b32 v254, s1, 27
	s_addc_u32 s0, s0, s21
	v_writelane_b32 v254, s0, 28
	s_nop 0
	v_readlane_b32 s2, v254, 11
	v_readlane_b32 s3, v254, 12
	s_nop 1
	v_cmp_gt_i64_e32 vcc, s[2:3], v[0:1]
	s_and_b64 s[0:1], vcc, exec
	s_cselect_b32 s1, s2, s4
	s_cselect_b32 s0, s3, s5
	s_add_u32 s1, s1, s20
	v_writelane_b32 v254, s1, 29
	s_addc_u32 s0, s0, s21
	v_writelane_b32 v254, s0, 30
	s_nop 0
	v_readlane_b32 s2, v254, 8
	v_readlane_b32 s3, v254, 9
	s_nop 1
	v_cmp_gt_i64_e32 vcc, s[2:3], v[0:1]
	s_and_b64 s[0:1], vcc, exec
	s_cselect_b32 s1, s2, s4
	s_cselect_b32 s0, s3, s5
	s_add_u32 s1, s1, s20
	v_writelane_b32 v254, s1, 31
	s_addc_u32 s0, s0, s21
	v_writelane_b32 v254, s0, 32
	s_nop 0
	v_readlane_b32 s2, v254, 5
	v_readlane_b32 s3, v254, 6
	s_nop 1
	v_cmp_gt_i64_e32 vcc, s[2:3], v[0:1]
	s_and_b64 s[0:1], vcc, exec
	s_cselect_b32 s0, s3, s5
	s_cselect_b32 s1, s2, s4
	v_readlane_b32 s2, v254, 2
	s_add_u32 s73, s1, s20
	v_readlane_b32 s3, v254, 3
	s_addc_u32 s74, s0, s21
	s_nop 0
	v_cmp_gt_i64_e32 vcc, s[2:3], v[0:1]
	s_and_b64 s[0:1], vcc, exec
	s_cselect_b32 s0, s3, s5
	s_cselect_b32 s1, s2, s4
	v_readlane_b32 s2, v255, 63
	s_add_u32 s75, s1, s20
	v_readlane_b32 s3, v254, 0
	s_addc_u32 s26, s0, s21
	s_nop 0
	v_cmp_gt_i64_e32 vcc, s[2:3], v[0:1]
	s_and_b64 s[0:1], vcc, exec
	s_cselect_b32 s0, s3, s5
	s_cselect_b32 s1, s2, s4
	v_readlane_b32 s2, v255, 60
	s_add_u32 s76, s1, s20
	v_readlane_b32 s3, v255, 61
	s_addc_u32 s77, s0, s21
	s_nop 0
	v_cmp_gt_i64_e32 vcc, s[2:3], v[0:1]
	s_and_b64 s[0:1], vcc, exec
	s_cselect_b32 s0, s3, s5
	s_cselect_b32 s1, s2, s4
	v_readlane_b32 s2, v253, 60
	s_add_u32 s78, s1, s20
	v_readlane_b32 s3, v253, 61
	s_addc_u32 s79, s0, s21
	s_nop 0
	v_cmp_gt_i64_e32 vcc, s[2:3], v[0:1]
	s_and_b64 s[0:1], vcc, exec
	s_cselect_b32 s0, s3, s5
	s_cselect_b32 s1, s2, s4
	v_readlane_b32 s2, v253, 62
	s_add_u32 s80, s1, s20
	v_readlane_b32 s3, v253, 63
	s_addc_u32 s81, s0, s21
	s_nop 0
	v_cmp_gt_i64_e32 vcc, s[2:3], v[0:1]
	s_and_b64 s[0:1], vcc, exec
	s_cselect_b32 s0, s3, s5
	s_cselect_b32 s1, s2, s4
	v_readlane_b32 s2, v255, 0
	s_add_u32 s82, s1, s20
	v_readlane_b32 s3, v255, 1
	s_addc_u32 s83, s0, s21
	s_nop 0
	v_cmp_gt_i64_e32 vcc, s[2:3], v[0:1]
	s_and_b64 s[0:1], vcc, exec
	s_cselect_b32 s0, s3, s5
	s_cselect_b32 s1, s2, s4
	v_readlane_b32 s2, v255, 2
	s_add_u32 s84, s1, s20
	v_readlane_b32 s3, v255, 3
	s_addc_u32 s85, s0, s21
	s_nop 0
	v_cmp_gt_i64_e32 vcc, s[2:3], v[0:1]
	s_and_b64 s[0:1], vcc, exec
	s_cselect_b32 s0, s3, s5
	s_cselect_b32 s1, s2, s4
	v_readlane_b32 s2, v255, 4
	s_add_u32 s86, s1, s20
	v_readlane_b32 s3, v255, 5
	s_addc_u32 s87, s0, s21
	s_nop 0
	v_cmp_gt_i64_e32 vcc, s[2:3], v[0:1]
	s_and_b64 s[0:1], vcc, exec
	s_cselect_b32 s0, s3, s5
	s_cselect_b32 s1, s2, s4
	v_readlane_b32 s2, v255, 6
	s_add_u32 s88, s1, s20
	v_readlane_b32 s3, v255, 7
	s_addc_u32 s89, s0, s21
	s_nop 0
	v_cmp_gt_i64_e32 vcc, s[2:3], v[0:1]
	s_and_b64 s[0:1], vcc, exec
	s_cselect_b32 s0, s3, s5
	s_cselect_b32 s1, s2, s4
	v_readlane_b32 s2, v255, 8
	s_add_u32 s90, s1, s20
	v_readlane_b32 s3, v255, 9
	s_addc_u32 s91, s0, s21
	s_nop 0
	v_cmp_gt_i64_e32 vcc, s[2:3], v[0:1]
	s_and_b64 s[0:1], vcc, exec
	s_cselect_b32 s0, s3, s5
	s_cselect_b32 s1, s2, s4
	v_readlane_b32 s2, v255, 10
	s_add_u32 s92, s1, s20
	v_readlane_b32 s3, v255, 11
	s_addc_u32 s93, s0, s21
	s_nop 0
	v_cmp_gt_i64_e32 vcc, s[2:3], v[0:1]
; __device__ __forceinline__ void pool_item(int l, int it, LAS unsigned char* lds, const bf16_t* PLB, bf16_t* YC, const float* pool_w, const float* pool_scale, int tid, int lane, int wave) {
;     ...
;         for (int ib = 0; ib < 48; ib += 12) {
;             unsigned raw[12]; const void* pp[12];
; #pragma unroll
;             for (int j = 0; j < 12; ++j) { const int off = ts - 15 + (ib + j < 47 ? ib + j : 46); pp[j] = PLB + (r0 + (pos0 + off >= 0 ? off : -pos0)) * BW; }
;             ld_u16_s12(raw, (unsigned)c * 2u, pp);
	s_and_b64 s[0:1], vcc, exec
	s_cselect_b32 s0, s3, s5
	s_cselect_b32 s1, s2, s4
	v_readlane_b32 s2, v255, 12
	s_add_u32 s94, s1, s20
	v_readlane_b32 s3, v255, 13
	s_addc_u32 s95, s0, s21
	s_nop 0
	v_cmp_gt_i64_e32 vcc, s[2:3], v[0:1]
	s_and_b64 s[0:1], vcc, exec
	s_cselect_b32 s0, s3, s5
	s_cselect_b32 s1, s2, s4
	v_readlane_b32 s2, v255, 14
	s_add_u32 s96, s1, s20
	v_readlane_b32 s3, v255, 15
	s_addc_u32 s97, s0, s21
	s_nop 0
	v_cmp_gt_i64_e32 vcc, s[2:3], v[0:1]
	s_and_b64 s[0:1], vcc, exec
	s_cselect_b32 s0, s3, s5
	s_cselect_b32 s1, s2, s4
	v_readlane_b32 s2, v255, 16
	s_add_u32 s40, s1, s20
	v_readlane_b32 s3, v255, 17
	s_addc_u32 s41, s0, s21
	s_nop 0
	v_cmp_gt_i64_e32 vcc, s[2:3], v[0:1]
	s_and_b64 s[0:1], vcc, exec
	s_cselect_b32 s0, s3, s5
	s_cselect_b32 s1, s2, s4
	v_readlane_b32 s2, v255, 18
	s_add_u32 s46, s1, s20
	v_readlane_b32 s3, v255, 19
	s_addc_u32 s47, s0, s21
	s_nop 0
	v_cmp_gt_i64_e32 vcc, s[2:3], v[0:1]
	s_and_b64 s[0:1], vcc, exec
	s_cselect_b32 s0, s3, s5
	s_cselect_b32 s1, s2, s4
	v_readlane_b32 s2, v255, 20
	s_add_u32 s48, s1, s20
	v_readlane_b32 s3, v255, 21
	s_addc_u32 s49, s0, s21
	s_nop 0
	v_cmp_gt_i64_e32 vcc, s[2:3], v[0:1]
	s_and_b64 s[0:1], vcc, exec
	s_cselect_b32 s0, s3, s5
	s_cselect_b32 s1, s2, s4
	v_readlane_b32 s2, v255, 22
	s_add_u32 s12, s1, s20
	v_readlane_b32 s3, v255, 23
	s_addc_u32 s13, s0, s21
	s_nop 0
	v_cmp_gt_i64_e32 vcc, s[2:3], v[0:1]
	s_and_b64 s[0:1], vcc, exec
	s_cselect_b32 s0, s3, s5
	s_cselect_b32 s1, s2, s4
	v_readlane_b32 s2, v255, 24
	s_add_u32 s6, s1, s20
	v_readlane_b32 s3, v255, 25
	s_addc_u32 s7, s0, s21
	s_nop 0
	v_cmp_gt_i64_e32 vcc, s[2:3], v[0:1]
	s_and_b64 s[0:1], vcc, exec
	s_cselect_b32 s0, s2, s4
	s_cselect_b32 s1, s3, s5
	s_add_u32 s2, s0, s20
	s_addc_u32 s3, s1, s21
	v_readlane_b32 s0, v255, 26
	v_readlane_b32 s1, v255, 27
	s_nop 1
	v_cmp_gt_i64_e32 vcc, s[0:1], v[0:1]
	s_and_b64 s[8:9], vcc, exec
	s_cselect_b32 s8, s1, s5
	s_cselect_b32 s9, s0, s4
	v_readlane_b32 s0, v255, 28
	s_add_u32 s66, s9, s20
	v_readlane_b32 s1, v255, 29
	s_addc_u32 s67, s8, s21
	s_nop 0
	v_cmp_gt_i64_e32 vcc, s[0:1], v[0:1]
	s_and_b64 s[8:9], vcc, exec
	s_cselect_b32 s8, s1, s5
	s_cselect_b32 s9, s0, s4
	v_readlane_b32 s0, v255, 30
	s_add_u32 s50, s9, s20
	v_readlane_b32 s1, v255, 31
	s_addc_u32 s51, s8, s21
	s_nop 0
	v_cmp_gt_i64_e32 vcc, s[0:1], v[0:1]
	s_and_b64 s[8:9], vcc, exec
	s_cselect_b32 s8, s1, s5
	s_cselect_b32 s9, s0, s4
	v_readlane_b32 s0, v255, 32
	s_add_u32 s52, s9, s20
	v_readlane_b32 s1, v255, 33
	s_addc_u32 s53, s8, s21
	s_nop 0
	v_cmp_gt_i64_e32 vcc, s[0:1], v[0:1]
	s_and_b64 s[8:9], vcc, exec
	s_cselect_b32 s8, s1, s5
	s_cselect_b32 s9, s0, s4
	v_readlane_b32 s0, v255, 34
	s_add_u32 s54, s9, s20
	v_readlane_b32 s1, v255, 35
	s_addc_u32 s55, s8, s21
	s_nop 0
	v_cmp_gt_i64_e32 vcc, s[0:1], v[0:1]
	s_and_b64 s[8:9], vcc, exec
	s_cselect_b32 s8, s1, s5
	s_cselect_b32 s9, s0, s4
	v_readlane_b32 s0, v255, 36
	s_add_u32 s62, s9, s20
	v_readlane_b32 s1, v255, 37
	s_addc_u32 s63, s8, s21
	s_nop 0
	v_cmp_gt_i64_e32 vcc, s[0:1], v[0:1]
	s_and_b64 s[8:9], vcc, exec
	s_cselect_b32 s8, s1, s5
	s_cselect_b32 s9, s0, s4
	v_readlane_b32 s0, v255, 38
	s_add_u32 s56, s9, s20
	v_readlane_b32 s1, v255, 39
	s_addc_u32 s57, s8, s21
	s_nop 0
	v_cmp_gt_i64_e32 vcc, s[0:1], v[0:1]
	s_and_b64 s[8:9], vcc, exec
	s_cselect_b32 s8, s1, s5
	s_cselect_b32 s9, s0, s4
	v_readlane_b32 s0, v255, 40
	s_add_u32 s36, s9, s20
	v_readlane_b32 s1, v255, 41
	s_addc_u32 s37, s8, s21
	s_nop 0
	v_cmp_gt_i64_e32 vcc, s[0:1], v[0:1]
	s_and_b64 s[8:9], vcc, exec
	s_cselect_b32 s8, s0, s4
	s_cselect_b32 s9, s1, s5
	s_add_u32 s8, s8, s20
	s_addc_u32 s9, s9, s21
	v_cmp_gt_i64_e32 vcc, s[4:5], v[2:3]
	s_and_b64 s[10:11], vcc, exec
	s_cselect_b32 s10, s4, s42
	v_readlane_b32 s0, v255, 42
	s_cselect_b32 s11, s5, s43
	s_add_u32 s10, s10, s20
	v_readlane_b32 s1, v255, 43
	s_addc_u32 s11, s11, s21
	s_nop 0
	v_cmp_gt_i64_e32 vcc, s[0:1], v[0:1]
	s_and_b64 vcc, vcc, exec
	s_cselect_b32 s14, s1, s5
	s_cselect_b32 s15, s0, s4
	v_readlane_b32 s0, v255, 44
	s_add_u32 s43, s15, s20
	v_readlane_b32 s1, v255, 45
	s_addc_u32 s33, s14, s21
	s_nop 0
	v_cmp_gt_i64_e32 vcc, s[0:1], v[0:1]
	s_and_b64 vcc, vcc, exec
	s_cselect_b32 s15, s0, s4
	s_cselect_b32 s14, s1, s5
	s_add_u32 s0, s15, s20
	s_addc_u32 s1, s14, s21
	v_cmp_gt_i64_e32 vcc, s[16:17], v[0:1]
	s_and_b64 vcc, vcc, exec
	s_cselect_b32 s14, s17, s5
	s_cselect_b32 s15, s16, s4
	v_readlane_b32 s16, v255, 48
	s_add_u32 s42, s15, s20
	v_readlane_b32 s17, v255, 49
	s_addc_u32 s27, s14, s21
	s_nop 0
	v_cmp_gt_i64_e32 vcc, s[16:17], v[0:1]
	s_and_b64 vcc, vcc, exec
	s_cselect_b32 s14, s17, s5
	s_cselect_b32 s15, s16, s4
	v_readlane_b32 s16, v255, 50
	s_add_u32 s38, s15, s20
	v_readlane_b32 s17, v255, 51
	s_addc_u32 s39, s14, s21
	s_nop 0
	v_cmp_gt_i64_e32 vcc, s[16:17], v[0:1]
	s_and_b64 vcc, vcc, exec
	s_cselect_b32 s15, s16, s4
	s_cselect_b32 s14, s17, s5
	s_add_u32 s15, s15, s20
	s_addc_u32 s14, s14, s21
	v_cmp_gt_i64_e32 vcc, s[18:19], v[0:1]
	s_and_b64 vcc, vcc, exec
	s_cselect_b32 s16, s19, s5
	s_cselect_b32 s17, s18, s4
	v_readlane_b32 s18, v255, 54
	s_add_u32 s44, s17, s20
	v_readlane_b32 s19, v255, 55
	s_addc_u32 s45, s16, s21
	s_nop 0
	v_cmp_gt_i64_e32 vcc, s[18:19], v[0:1]
	s_and_b64 vcc, vcc, exec
	s_cselect_b32 s17, s18, s4
	s_cselect_b32 s16, s19, s5
	s_add_u32 s18, s17, s20
	s_addc_u32 s19, s16, s21
	v_cmp_gt_i64_e32 vcc, s[68:69], v[0:1]
	s_and_b64 vcc, vcc, exec
	s_cselect_b32 s16, s69, s5
	s_cselect_b32 s17, s68, s4
	v_readlane_b32 s68, v255, 58
	s_add_u32 s17, s17, s20
	v_readlane_b32 s69, v255, 59
	s_addc_u32 s16, s16, s21
	s_nop 0
	v_cmp_gt_i64_e32 vcc, s[68:69], v[0:1]
; __device__ __forceinline__ void pool_item(int l, int it, LAS unsigned char* lds, const bf16_t* PLB, bf16_t* YC, const float* pool_w, const float* pool_scale, int tid, int lane, int wave) {
;     ...
;         for (int ib = 0; ib < 48; ib += 12) {
;             unsigned raw[12]; const void* pp[12];
; #pragma unroll
;             for (int j = 0; j < 12; ++j) { const int off = ts - 15 + (ib + j < 47 ? ib + j : 46); pp[j] = PLB + (r0 + (pos0 + off >= 0 ? off : -pos0)) * BW; }
;             ld_u16_s12(raw, (unsigned)c * 2u, pp);
	s_and_b64 vcc, vcc, exec
	s_cselect_b32 s4, s68, s4
	s_cselect_b32 s5, s69, s5
	s_add_u32 vcc_lo, s4, s20
	s_addc_u32 vcc_hi, s5, s21
	s_add_u32 s4, s28, s30
	s_addc_u32 s5, s29, s31
	s_lshl_b64 s[4:5], s[4:5], 9
	s_add_u32 s4, s35, s4
	s_addc_u32 s5, s34, s5
	s_add_u32 s22, s28, s22
	s_addc_u32 s23, s29, s23
	s_lshl_b64 s[22:23], s[22:23], 9
	s_add_u32 s22, s35, s22
	s_addc_u32 s23, s34, s23
	s_add_u32 s24, s28, s24
	s_addc_u32 s25, s29, s25
	s_lshl_b64 s[24:25], s[24:25], 9
	s_add_u32 s24, s35, s24
	s_addc_u32 s25, s34, s25
	s_add_u32 s30, s28, s58
	s_addc_u32 s31, s29, s59
	s_lshl_b64 s[30:31], s[30:31], 9
	s_add_u32 s30, s35, s30
	s_addc_u32 s31, s34, s31
	s_add_u32 s58, s28, s64
	s_addc_u32 s59, s29, s65
	s_lshl_b64 s[58:59], s[58:59], 9
	s_add_u32 s58, s35, s58
	s_addc_u32 s59, s34, s59
	s_add_u32 s60, s28, s60
	s_addc_u32 s61, s29, s61
	s_lshl_b64 s[60:61], s[60:61], 9
	s_add_u32 s60, s35, s60
	s_addc_u32 s61, s34, s61
	s_add_u32 s64, s28, vcc_lo
	s_addc_u32 s65, s29, vcc_hi
	s_lshl_b64 s[64:65], s[64:65], 9
	s_add_u32 s64, s35, s64
	s_addc_u32 s65, s34, s65
	s_add_u32 vcc_lo, s28, s17
	s_addc_u32 vcc_hi, s29, s16
	s_lshl_b64 vcc, vcc, 9
	s_add_u32 s16, s35, vcc_lo
	s_addc_u32 s17, s34, vcc_hi
	s_add_u32 vcc_lo, s28, s18
	s_addc_u32 vcc_hi, s29, s19
	s_lshl_b64 vcc, vcc, 9
	s_add_u32 s18, s35, vcc_lo
	s_addc_u32 s19, s34, vcc_hi
	s_add_u32 vcc_lo, s28, s44
	s_addc_u32 vcc_hi, s29, s45
	s_lshl_b64 vcc, vcc, 9
	s_add_u32 s44, s35, vcc_lo
	s_addc_u32 s45, s34, vcc_hi
	s_add_u32 vcc_lo, s28, s15
	s_addc_u32 vcc_hi, s29, s14
	s_lshl_b64 vcc, vcc, 9
	s_add_u32 s14, s35, vcc_lo
	s_addc_u32 s15, s34, vcc_hi
	s_add_u32 vcc_lo, s28, s38
	s_addc_u32 vcc_hi, s29, s39
	s_lshl_b64 vcc, vcc, 9
	s_add_u32 s38, s35, vcc_lo
	s_addc_u32 s39, s34, vcc_hi
	s_nop 4
	global_load_ushort v53, v33, s[4:5]
	global_load_ushort v54, v33, s[22:23]
	global_load_ushort v55, v33, s[24:25]
	global_load_ushort v56, v33, s[30:31]
	global_load_ushort v57, v33, s[58:59]
	global_load_ushort v58, v33, s[60:61]
	global_load_ushort v59, v33, s[64:65]
	global_load_ushort v60, v33, s[16:17]
	global_load_ushort v52, v33, s[18:19]
	global_load_ushort v51, v33, s[44:45]
	global_load_ushort v50, v33, s[14:15]
	global_load_ushort v49, v33, s[38:39]
	s_cmp_eq_u64 s[4:5], s[22:23]
	s_cselect_b32 s98, 0x1e00, 0
	s_sub_u32 s98, s4, s98
	s_subb_u32 s99, s5, 0
	s_add_u32 s98, s98, 0x1800
	s_addc_u32 s99, s99, 0
	global_load_ushort v11, v33, s[98:99]
	s_add_u32 s98, s98, 0x200
	s_addc_u32 s99, s99, 0
	global_load_ushort v10, v33, s[98:99]
	s_add_u32 s98, s98, 0x200
	s_addc_u32 s99, s99, 0
	global_load_ushort v9, v33, s[98:99]
	s_add_u32 s98, s98, 0x200
	s_addc_u32 s99, s99, 0
	global_load_ushort v8, v33, s[98:99]
	s_add_u32 s98, s98, 0x200
	s_addc_u32 s99, s99, 0
	global_load_ushort v7, v33, s[98:99]
	s_add_u32 s98, s98, 0x200
	s_addc_u32 s99, s99, 0
	global_load_ushort v6, v33, s[98:99]
	s_add_u32 s98, s98, 0x200
	s_addc_u32 s99, s99, 0
	global_load_ushort v5, v33, s[98:99]
	s_add_u32 s98, s98, 0x200
	s_addc_u32 s99, s99, 0
	global_load_ushort v4, v33, s[98:99]
	s_add_u32 s98, s98, 0x200
	s_addc_u32 s99, s99, 0
	global_load_ushort v3, v33, s[98:99]
	s_add_u32 s98, s98, 0x200
	s_addc_u32 s99, s99, 0
	global_load_ushort v2, v33, s[98:99]
	s_add_u32 s98, s98, 0x200
	s_addc_u32 s99, s99, 0
	global_load_ushort v1, v33, s[98:99]
	s_add_u32 s98, s98, 0x200
	s_addc_u32 s99, s99, 0
	global_load_ushort v0, v33, s[98:99]
	s_add_u32 s98, s98, 0x200
	s_addc_u32 s99, s99, 0
	global_load_ushort v22, v33, s[98:99]
	s_add_u32 s98, s98, 0x200
	s_addc_u32 s99, s99, 0
	global_load_ushort v21, v33, s[98:99]
	s_add_u32 s98, s98, 0x200
	s_addc_u32 s99, s99, 0
	global_load_ushort v20, v33, s[98:99]
	s_add_u32 s98, s98, 0x200
	s_addc_u32 s99, s99, 0
	global_load_ushort v19, v33, s[98:99]
	s_add_u32 s98, s98, 0x200
	s_addc_u32 s99, s99, 0
	global_load_ushort v18, v33, s[98:99]
	s_add_u32 s98, s98, 0x200
	s_addc_u32 s99, s99, 0
	global_load_ushort v17, v33, s[98:99]
	s_add_u32 s98, s98, 0x200
	s_addc_u32 s99, s99, 0
	global_load_ushort v16, v33, s[98:99]
	s_add_u32 s98, s98, 0x200
	s_addc_u32 s99, s99, 0
	global_load_ushort v15, v33, s[98:99]
	s_add_u32 s98, s98, 0x200
	s_addc_u32 s99, s99, 0
	global_load_ushort v14, v33, s[98:99]
	s_add_u32 s98, s98, 0x200
	s_addc_u32 s99, s99, 0
	global_load_ushort v13, v33, s[98:99]
	s_add_u32 s98, s98, 0x200
	s_addc_u32 s99, s99, 0
	global_load_ushort v12, v33, s[98:99]
	s_add_u32 s98, s98, 0x200
	s_addc_u32 s99, s99, 0
	global_load_ushort v61, v33, s[98:99]
	s_add_u32 s98, s98, 0x200
	s_addc_u32 s99, s99, 0
	global_load_ushort v72, v33, s[98:99]
	s_add_u32 s98, s98, 0x200
	s_addc_u32 s99, s99, 0
	global_load_ushort v71, v33, s[98:99]
	s_add_u32 s98, s98, 0x200
	s_addc_u32 s99, s99, 0
	global_load_ushort v70, v33, s[98:99]
	s_add_u32 s98, s98, 0x200
	s_addc_u32 s99, s99, 0
	global_load_ushort v69, v33, s[98:99]
	s_add_u32 s98, s98, 0x200
	s_addc_u32 s99, s99, 0
	global_load_ushort v68, v33, s[98:99]
	s_add_u32 s98, s98, 0x200
	s_addc_u32 s99, s99, 0
	global_load_ushort v67, v33, s[98:99]
	s_add_u32 s98, s98, 0x200
	s_addc_u32 s99, s99, 0
	global_load_ushort v66, v33, s[98:99]
	s_add_u32 s98, s98, 0x200
	s_addc_u32 s99, s99, 0
	global_load_ushort v65, v33, s[98:99]
	s_add_u32 s98, s98, 0x200
	s_addc_u32 s99, s99, 0
	global_load_ushort v64, v33, s[98:99]
	s_add_u32 s98, s98, 0x200
	s_addc_u32 s99, s99, 0
	global_load_ushort v63, v33, s[98:99]
	s_add_u32 s98, s98, 0x200
	s_addc_u32 s99, s99, 0
	global_load_ushort v62, v33, s[98:99]
	global_load_ushort v23, v33, s[98:99]
	s_waitcnt vmcnt(36)
; __device__ __forceinline__ void pool_item(int l, int it, LAS unsigned char* lds, const bf16_t* PLB, bf16_t* YC, const float* pool_w, const float* pool_scale, int tid, int lane, int wave) {
;     ...
;         for (int ib = 0; ib < 48; ib += 12) {
;             unsigned raw[12]; const void* pp[12];
; #pragma unroll
;             for (int j = 0; j < 12; ++j) { const int off = ts - 15 + (ib + j < 47 ? ib + j : 46); pp[j] = PLB + (r0 + (pos0 + off >= 0 ? off : -pos0)) * BW; }
;             ld_u16_s12(raw, (unsigned)c * 2u, pp);
	s_add_u32 s4, s28, s42
	s_addc_u32 s5, s29, s27
	s_lshl_b64 s[4:5], s[4:5], 9
	s_add_u32 s4, s35, s4
	s_addc_u32 s5, s34, s5
	s_add_u32 s14, s28, s0
	s_addc_u32 s15, s29, s1
	s_lshl_b64 s[14:15], s[14:15], 9
	s_add_u32 s22, s35, s14
	s_addc_u32 s23, s34, s15
	s_add_u32 s14, s28, s43
	s_addc_u32 s15, s29, s33
	s_lshl_b64 s[14:15], s[14:15], 9
	s_add_u32 s24, s35, s14
	s_addc_u32 s25, s34, s15
	s_add_u32 s10, s28, s10
	s_addc_u32 s11, s29, s11
	s_lshl_b64 s[10:11], s[10:11], 9
	s_add_u32 s10, s35, s10
	s_addc_u32 s11, s34, s11
	s_add_u32 s8, s28, s8
	s_addc_u32 s9, s29, s9
	s_lshl_b64 s[8:9], s[8:9], 9
	s_add_u32 s8, s35, s8
	s_addc_u32 s9, s34, s9
	s_add_u32 s14, s28, s36
	s_addc_u32 s15, s29, s37
	s_lshl_b64 s[14:15], s[14:15], 9
	s_add_u32 s14, s35, s14
	s_addc_u32 s15, s34, s15
	s_add_u32 s16, s28, s56
	s_addc_u32 s17, s29, s57
	s_lshl_b64 s[16:17], s[16:17], 9
	s_add_u32 s16, s35, s16
	s_addc_u32 s17, s34, s17
	s_add_u32 s18, s28, s62
	s_addc_u32 s19, s29, s63
	s_lshl_b64 s[18:19], s[18:19], 9
	s_add_u32 s18, s35, s18
	s_addc_u32 s19, s34, s19
	s_add_u32 s30, s28, s54
	s_addc_u32 s31, s29, s55
	s_lshl_b64 s[30:31], s[30:31], 9
	s_add_u32 s30, s35, s30
	s_addc_u32 s31, s34, s31
	s_add_u32 s36, s28, s52
	s_addc_u32 s37, s29, s53
	s_lshl_b64 s[36:37], s[36:37], 9
	s_add_u32 s36, s35, s36
	s_addc_u32 s37, s34, s37
	s_add_u32 s38, s28, s50
	s_addc_u32 s39, s29, s51
	s_lshl_b64 s[38:39], s[38:39], 9
	s_add_u32 s38, s35, s38
	s_addc_u32 s39, s34, s39
	s_add_u32 s44, s28, s66
	s_addc_u32 s45, s29, s67
	s_lshl_b64 s[44:45], s[44:45], 9
	s_add_u32 s44, s35, s44
	s_addc_u32 s45, s34, s45
	s_add_u32 s0, s28, s2
	s_addc_u32 s1, s29, s3
	s_lshl_b64 s[0:1], s[0:1], 9
	s_waitcnt vmcnt(24)
	s_add_u32 s4, s35, s0
	s_addc_u32 s5, s34, s1
	s_add_u32 s0, s28, s6
	s_addc_u32 s1, s29, s7
	s_lshl_b64 s[0:1], s[0:1], 9
	s_add_u32 s22, s35, s0
	s_addc_u32 s23, s34, s1
	s_add_u32 s0, s28, s12
	s_addc_u32 s1, s29, s13
	s_lshl_b64 s[0:1], s[0:1], 9
	s_add_u32 s24, s35, s0
	s_addc_u32 s25, s34, s1
	s_add_u32 s0, s28, s48
	s_addc_u32 s1, s29, s49
	s_lshl_b64 s[0:1], s[0:1], 9
	s_add_u32 s0, s35, s0
	s_addc_u32 s1, s34, s1
	s_add_u32 s2, s28, s46
	s_addc_u32 s3, s29, s47
	s_lshl_b64 s[2:3], s[2:3], 9
	s_add_u32 s2, s35, s2
	s_addc_u32 s3, s34, s3
	s_add_u32 s6, s28, s40
	s_addc_u32 s7, s29, s41
	s_lshl_b64 s[6:7], s[6:7], 9
	s_add_u32 s6, s35, s6
	s_addc_u32 s7, s34, s7
	s_add_u32 s8, s28, s96
	s_addc_u32 s9, s29, s97
	s_lshl_b64 s[8:9], s[8:9], 9
	s_add_u32 s8, s35, s8
	s_addc_u32 s9, s34, s9
	s_add_u32 s10, s28, s94
	s_addc_u32 s11, s29, s95
	s_lshl_b64 s[10:11], s[10:11], 9
	s_add_u32 s10, s35, s10
	s_addc_u32 s11, s34, s11
	s_add_u32 s14, s28, s92
	s_addc_u32 s15, s29, s93
	s_lshl_b64 s[14:15], s[14:15], 9
	s_add_u32 s14, s35, s14
	s_addc_u32 s15, s34, s15
	s_add_u32 s16, s28, s90
	s_addc_u32 s17, s29, s91
	s_lshl_b64 s[16:17], s[16:17], 9
	s_add_u32 s16, s35, s16
	s_addc_u32 s17, s34, s17
	s_add_u32 s18, s28, s88
	s_addc_u32 s19, s29, s89
	s_lshl_b64 s[18:19], s[18:19], 9
	s_add_u32 s18, s35, s18
	s_addc_u32 s19, s34, s19
	s_add_u32 s30, s28, s86
	s_addc_u32 s31, s29, s87
	s_lshl_b64 s[30:31], s[30:31], 9
	s_add_u32 s30, s35, s30
	s_addc_u32 s31, s34, s31
	s_waitcnt vmcnt(12)
	s_add_u32 s0, s28, s84
	s_addc_u32 s1, s29, s85
	s_lshl_b64 s[0:1], s[0:1], 9
	s_add_u32 s4, s35, s0
	s_addc_u32 s5, s34, s1
	s_add_u32 s0, s28, s82
	s_addc_u32 s1, s29, s83
	s_lshl_b64 s[0:1], s[0:1], 9
	s_add_u32 s0, s35, s0
	s_addc_u32 s1, s34, s1
	s_add_u32 s2, s28, s80
	s_addc_u32 s3, s29, s81
	s_lshl_b64 s[2:3], s[2:3], 9
	s_add_u32 s2, s35, s2
	s_addc_u32 s3, s34, s3
	s_add_u32 s6, s28, s78
	s_addc_u32 s7, s29, s79
	s_lshl_b64 s[6:7], s[6:7], 9
	s_add_u32 s6, s35, s6
	s_addc_u32 s7, s34, s7
	s_add_u32 s8, s28, s76
	s_addc_u32 s9, s29, s77
	s_lshl_b64 s[8:9], s[8:9], 9
	s_add_u32 s8, s35, s8
	s_addc_u32 s9, s34, s9
	s_add_u32 s10, s28, s75
	s_addc_u32 s11, s29, s26
	s_lshl_b64 s[10:11], s[10:11], 9
	s_add_u32 s10, s35, s10
	s_addc_u32 s11, s34, s11
	s_add_u32 s14, s28, s73
	s_addc_u32 s15, s29, s74
	s_lshl_b64 s[14:15], s[14:15], 9
	s_add_u32 s14, s35, s14
	s_addc_u32 s15, s34, s15
	v_readlane_b32 s12, v254, 31
	s_add_u32 s16, s28, s12
	v_readlane_b32 s12, v254, 32
	s_addc_u32 s17, s29, s12
	s_lshl_b64 s[16:17], s[16:17], 9
	s_add_u32 s16, s35, s16
	s_addc_u32 s17, s34, s17
	v_readlane_b32 s12, v254, 29
	s_add_u32 s18, s28, s12
	v_readlane_b32 s12, v254, 30
	s_addc_u32 s19, s29, s12
	s_lshl_b64 s[18:19], s[18:19], 9
	s_add_u32 s18, s35, s18
	s_addc_u32 s19, s34, s19
	v_readlane_b32 s12, v254, 27
	s_add_u32 s22, s28, s12
	v_readlane_b32 s12, v254, 28
	s_addc_u32 s23, s29, s12
	s_lshl_b64 s[22:23], s[22:23], 9
	s_add_u32 s22, s35, s22
	s_addc_u32 s23, s34, s23
	v_readlane_b32 s12, v254, 25
	s_add_u32 s12, s28, s12
	v_readlane_b32 s13, v254, 26
	s_addc_u32 s13, s29, s13
	s_lshl_b64 s[12:13], s[12:13], 9
	s_add_u32 s12, s35, s12
	s_addc_u32 s13, s34, s13
	s_waitcnt vmcnt(0)
; #define POOL_WIN(WIN) do { _Pragma("unroll") for (int t = 0; t < 32; ++t) { float s = 0.f; _Pragma("unroll") for (int j = 0; j < WIN; ++j) s += x[15 + t - j]; \
;             const int pos = pos0 + ts + t; const float cnt = (float)(pos + 1 < WIN ? pos + 1 : WIN); pl[(ts + t) * PS + c] = f2bf(s / cnt - x[15 + t]); } } while (0)
; __device__ __forceinline__ void pool_item(int l, int it, LAS unsigned char* lds, const bf16_t* PLB, bf16_t* YC, const float* pool_w, const float* pool_scale, int tid, int lane, int wave) {
;     ...
; #pragma unroll
;             for (int j = 0; j < 12; ++j) if (ib + j < 47) x[ib + j] = (pos0 + ts - 15 + ib + j >= 0) ? __uint_as_float(raw[j] << 16) : 0.f;
;         }
;     ...
;         if (g == 0) POOL_WIN(2); else if (g == 1) POOL_WIN(4); else if (g == 2) POOL_WIN(8); else POOL_WIN(16);
	s_add_i32 s22, s72, s70
	s_or_b32 s24, s22, 12
	s_cmp_gt_i32 s24, 14
	v_lshlrev_b32_e32 v11, 16, v11
	s_cselect_b64 vcc, -1, 0
	s_cmp_gt_i32 s24, 13
	v_cndmask_b32_e32 v48, 0, v11, vcc
	v_lshlrev_b32_e32 v10, 16, v10
	s_cselect_b64 vcc, -1, 0
	s_cmp_gt_i32 s22, 0
	v_cndmask_b32_e32 v47, 0, v10, vcc
	s_cselect_b64 vcc, -1, 0
	s_cmp_gt_i32 s22, -1
	s_cselect_b64 s[4:5], -1, 0
	v_lshlrev_b32_e32 v0, 16, v0
	v_cndmask_b32_e64 v23, 0, v0, s[4:5]
	v_lshlrev_b32_e32 v0, 16, v22
	v_cndmask_b32_e64 v22, 0, v0, s[4:5]
	v_lshlrev_b32_e32 v0, 16, v21
	v_cndmask_b32_e64 v21, 0, v0, s[4:5]
	v_lshlrev_b32_e32 v0, 16, v20
	v_cndmask_b32_e64 v20, 0, v0, s[4:5]
	v_lshlrev_b32_e32 v0, 16, v19
	v_cndmask_b32_e64 v19, 0, v0, s[4:5]
	v_lshlrev_b32_e32 v0, 16, v18
	v_cndmask_b32_e64 v18, 0, v0, s[4:5]
	v_lshlrev_b32_e32 v0, 16, v17
	v_cndmask_b32_e64 v17, 0, v0, s[4:5]
	v_lshlrev_b32_e32 v0, 16, v16
	v_cndmask_b32_e64 v16, 0, v0, s[4:5]
	v_lshlrev_b32_e32 v0, 16, v15
	v_cndmask_b32_e64 v15, 0, v0, s[4:5]
	v_lshlrev_b32_e32 v0, 16, v14
	v_cndmask_b32_e64 v14, 0, v0, s[4:5]
	v_lshlrev_b32_e32 v0, 16, v13
	s_or_b32 s23, s22, 24
	v_cndmask_b32_e64 v13, 0, v0, s[4:5]
	v_lshlrev_b32_e32 v0, 16, v12
	v_lshlrev_b32_e32 v8, 16, v8
	v_lshlrev_b32_e32 v7, 16, v7
	v_lshlrev_b32_e32 v6, 16, v6
	v_lshlrev_b32_e32 v5, 16, v5
	v_lshlrev_b32_e32 v4, 16, v4
	v_lshlrev_b32_e32 v3, 16, v3
	v_lshlrev_b32_e32 v2, 16, v2
	v_lshlrev_b32_e32 v1, 16, v1
	v_cndmask_b32_e64 v12, 0, v0, s[4:5]
	v_lshlrev_b32_e32 v0, 16, v61
	s_cmpk_gt_i32 s22, 0xffea
	v_cndmask_b32_e64 v31, 0, v8, s[4:5]
	v_cndmask_b32_e64 v30, 0, v7, s[4:5]
	v_cndmask_b32_e64 v29, 0, v6, s[4:5]
	v_cndmask_b32_e64 v28, 0, v5, s[4:5]
	v_cndmask_b32_e64 v27, 0, v4, s[4:5]
	v_cndmask_b32_e64 v26, 0, v3, s[4:5]
	v_cndmask_b32_e64 v25, 0, v2, s[4:5]
	v_cndmask_b32_e64 v24, 0, v1, s[4:5]
	v_cndmask_b32_e64 v11, 0, v0, s[4:5]
	v_lshlrev_b32_e32 v0, 16, v72
	s_cselect_b64 s[4:5], -1, 0
	s_cmpk_gt_i32 s22, 0xffe9
	v_lshlrev_b32_e32 v9, 16, v9
	v_cndmask_b32_e64 v10, 0, v0, s[4:5]
	v_lshlrev_b32_e32 v0, 16, v71
	s_cselect_b64 s[4:5], -1, 0
	s_cmpk_gt_i32 s22, 0xffe8
	v_cndmask_b32_e32 v46, 0, v9, vcc
	v_cndmask_b32_e64 v9, 0, v0, s[4:5]
	v_lshlrev_b32_e32 v0, 16, v70
	s_cselect_b64 s[4:5], -1, 0
	s_cmpk_gt_i32 s22, 0xffe7
	v_cndmask_b32_e64 v8, 0, v0, s[4:5]
	v_lshlrev_b32_e32 v0, 16, v69
	s_cselect_b64 s[4:5], -1, 0
	s_cmpk_gt_i32 s22, 0xffe6
	v_cndmask_b32_e64 v7, 0, v0, s[4:5]
	v_lshlrev_b32_e32 v0, 16, v68
	s_cselect_b64 s[4:5], -1, 0
	s_cmpk_gt_i32 s22, 0xffe5
	v_cndmask_b32_e64 v6, 0, v0, s[4:5]
	v_lshlrev_b32_e32 v0, 16, v67
	s_cselect_b64 s[4:5], -1, 0
	s_cmpk_gt_i32 s22, 0xffe4
	v_cndmask_b32_e64 v5, 0, v0, s[4:5]
	v_lshlrev_b32_e32 v0, 16, v66
	s_cselect_b64 s[4:5], -1, 0
	s_cmpk_gt_i32 s22, 0xffe3
	v_cndmask_b32_e64 v4, 0, v0, s[4:5]
	v_lshlrev_b32_e32 v0, 16, v65
	s_cselect_b64 s[4:5], -1, 0
	s_cmpk_gt_i32 s22, 0xffe2
	v_cndmask_b32_e64 v1, 0, v0, s[4:5]
	v_lshlrev_b32_e32 v0, 16, v64
	s_cselect_b64 s[4:5], -1, 0
	s_cmpk_gt_i32 s22, 0xffe1
	v_cndmask_b32_e64 v2, 0, v0, s[4:5]
	v_lshlrev_b32_e32 v0, 16, v63
	s_cselect_b64 s[4:5], -1, 0
	s_cmpk_gt_i32 s22, 0xffe0
	v_cndmask_b32_e64 v3, 0, v0, s[4:5]
	v_lshlrev_b32_e32 v0, 16, v62
	s_cselect_b64 s[4:5], -1, 0
	v_readlane_b32 s0, v253, 32
	v_cndmask_b32_e64 v0, 0, v0, s[4:5]
	s_cmp_lt_i32 s0, 2
	s_mov_b64 s[4:5], -1
	v_readlane_b32 s96, v254, 20
	s_mov_b64 s[42:43], s[70:71]
	v_readlane_b32 s3, v254, 24
	v_readlane_b32 s97, v254, 21
	s_cbranch_scc1 .LBB0_93
	s_cmp_gt_i32 s22, 6
	v_lshlrev_b32_e32 v52, 16, v52
	s_cselect_b64 s[4:5], -1, 0
	s_cmp_gt_i32 s22, 5
	v_cndmask_b32_e64 v52, 0, v52, s[4:5]
	v_lshlrev_b32_e32 v51, 16, v51
	s_cselect_b64 s[4:5], -1, 0
	s_cmp_gt_i32 s22, 4
	v_cndmask_b32_e64 v51, 0, v51, s[4:5]
	v_lshlrev_b32_e32 v50, 16, v50
	s_cselect_b64 s[4:5], -1, 0
	s_cmp_gt_i32 s22, 3
	v_cndmask_b32_e64 v50, 0, v50, s[4:5]
	v_lshlrev_b32_e32 v49, 16, v49
	s_cselect_b64 s[4:5], -1, 0
	v_readlane_b32 s0, v253, 32
	v_cndmask_b32_e64 v49, 0, v49, s[4:5]
	s_cmp_gt_i32 s0, 2
	s_mov_b64 s[4:5], -1
	s_cbranch_scc0 .LBB0_90
	v_add_f32_e32 v61, 0, v31
	v_add_f32_e32 v61, v46, v61
	v_add_f32_e32 v61, v47, v61
	s_cmp_gt_i32 s22, 7
	v_add_f32_e32 v61, v48, v61
	v_lshlrev_b32_e32 v60, 16, v60
	s_cselect_b64 s[4:5], -1, 0
	s_cmp_gt_i32 s22, 8
	v_add_f32_e32 v61, v49, v61
	v_cndmask_b32_e64 v60, 0, v60, s[4:5]
	v_lshlrev_b32_e32 v59, 16, v59
	s_cselect_b64 s[4:5], -1, 0
	s_cmp_gt_i32 s22, 9
	v_add_f32_e32 v61, v50, v61
	v_cndmask_b32_e64 v59, 0, v59, s[4:5]
	v_lshlrev_b32_e32 v58, 16, v58
	s_cselect_b64 s[4:5], -1, 0
	s_cmp_gt_i32 s22, 10
	v_add_f32_e32 v61, v51, v61
	v_cndmask_b32_e64 v58, 0, v58, s[4:5]
	v_lshlrev_b32_e32 v57, 16, v57
	s_cselect_b64 s[4:5], -1, 0
	s_cmp_gt_i32 s22, 11
	v_add_f32_e32 v61, v52, v61
	v_cndmask_b32_e64 v57, 0, v57, s[4:5]
	v_lshlrev_b32_e32 v56, 16, v56
	s_cselect_b64 s[4:5], -1, 0
	s_cmp_gt_i32 s22, 12
	v_add_f32_e32 v61, v60, v61
	v_cndmask_b32_e64 v56, 0, v56, s[4:5]
	v_lshlrev_b32_e32 v55, 16, v55
	s_cselect_b64 s[4:5], -1, 0
	s_cmp_gt_i32 s22, 13
	v_add_f32_e32 v61, v59, v61
	v_cndmask_b32_e64 v55, 0, v55, s[4:5]
	s_cselect_b64 s[4:5], -1, 0
	v_add_f32_e32 v61, v58, v61
	s_min_i32 s0, s22, 15
	v_add_f32_e32 v61, v57, v61
	s_add_i32 s0, s0, 1
	v_lshlrev_b32_e32 v54, 16, v54
	v_add_f32_e32 v61, v56, v61
	v_cvt_f32_i32_e32 v62, s0
	v_cndmask_b32_e64 v54, 0, v54, s[4:5]
	v_lshlrev_b32_e32 v53, 16, v53
	v_add_f32_e32 v61, v55, v61
	v_cndmask_b32_e32 v53, 0, v53, vcc
	v_add_f32_e32 v61, v54, v61
	v_add_f32_e32 v53, v53, v61
	v_div_scale_f32 v61, s[0:1], v62, v62, v53
	v_rcp_f32_e32 v63, v61
	s_or_b32 s0, s22, 1
	s_min_i32 s0, s0, 15
	s_add_i32 s0, s0, 1
	v_fma_f32 v64, -v61, v63, 1.0
	v_fmac_f32_e32 v63, v64, v63
	v_div_scale_f32 v64, vcc, v53, v62, v53
	v_mul_f32_e32 v65, v64, v63
	v_fma_f32 v66, -v61, v65, v64
	v_fmac_f32_e32 v65, v66, v63
	v_fma_f32 v61, -v61, v65, v64
	v_div_fmas_f32 v61, v61, v63, v65
	v_div_fixup_f32 v53, v61, v62, v53
	v_add_f32_e32 v61, 0, v30
	v_add_f32_e32 v61, v31, v61
	v_add_f32_e32 v61, v46, v61
	v_add_f32_e32 v61, v47, v61
	v_add_f32_e32 v61, v48, v61
	v_add_f32_e32 v61, v49, v61
	v_add_f32_e32 v61, v50, v61
	v_add_f32_e32 v61, v51, v61
	v_add_f32_e32 v61, v52, v61
	v_add_f32_e32 v61, v60, v61
	v_add_f32_e32 v61, v59, v61
	v_add_f32_e32 v61, v58, v61
	v_add_f32_e32 v61, v57, v61
	v_cvt_f32_i32_e32 v62, s0
	v_add_f32_e32 v61, v56, v61
	v_add_f32_e32 v61, v55, v61
	v_add_f32_e32 v54, v54, v61
	v_div_scale_f32 v61, s[0:1], v62, v62, v54
	v_rcp_f32_e32 v63, v61
	v_sub_f32_e32 v53, v53, v31
	v_readlane_b32 s0, v253, 41
	v_cvt_pk_bf16_f32 v53, v53, v53
	s_mov_b64 s[4:5], 0
	s_nop 0
	v_add_u32_e32 v64, s0, v43
	ds_write_b16 v64, v53
	v_fma_f32 v53, -v61, v63, 1.0
	v_fmac_f32_e32 v63, v53, v63
	v_div_scale_f32 v53, vcc, v54, v62, v54
	v_mul_f32_e32 v65, v53, v63
	v_fma_f32 v66, -v61, v65, v53
	v_fmac_f32_e32 v65, v66, v63
	v_fma_f32 v53, -v61, v65, v53
	v_div_fmas_f32 v53, v53, v63, v65
	v_div_fixup_f32 v53, v53, v62, v54
	v_add_f32_e32 v54, 0, v29
	v_add_f32_e32 v54, v30, v54
	v_add_f32_e32 v54, v31, v54
	v_add_f32_e32 v54, v46, v54
	v_add_f32_e32 v54, v47, v54
	v_add_f32_e32 v54, v48, v54
	v_add_f32_e32 v54, v49, v54
	v_add_f32_e32 v54, v50, v54
	v_add_f32_e32 v54, v51, v54
	v_add_f32_e32 v54, v52, v54
	s_or_b32 s0, s22, 2
	v_add_f32_e32 v54, v60, v54
	s_min_i32 s0, s0, 15
	v_add_f32_e32 v54, v59, v54
	s_add_i32 s0, s0, 1
	v_add_f32_e32 v54, v58, v54
	v_cvt_f32_i32_e32 v61, s0
	v_add_f32_e32 v54, v57, v54
	v_add_f32_e32 v54, v56, v54
	v_add_f32_e32 v54, v55, v54
	v_div_scale_f32 v55, s[0:1], v61, v61, v54
	v_rcp_f32_e32 v62, v55
	v_sub_f32_e32 v53, v53, v30
	v_cvt_pk_bf16_f32 v53, v53, v53
	ds_write_b16 v64, v53 offset:528
	v_fma_f32 v53, -v55, v62, 1.0
	v_fmac_f32_e32 v62, v53, v62
	v_div_scale_f32 v53, vcc, v54, v61, v54
	v_mul_f32_e32 v63, v53, v62
	v_fma_f32 v65, -v55, v63, v53
	v_fmac_f32_e32 v63, v65, v62
	v_fma_f32 v53, -v55, v63, v53
	v_div_fmas_f32 v53, v53, v62, v63
	v_div_fixup_f32 v53, v53, v61, v54
	v_add_f32_e32 v54, 0, v28
	v_add_f32_e32 v54, v29, v54
	v_add_f32_e32 v54, v30, v54
	v_add_f32_e32 v54, v31, v54
	v_add_f32_e32 v54, v46, v54
	v_add_f32_e32 v54, v47, v54
	v_add_f32_e32 v54, v48, v54
	v_add_f32_e32 v54, v49, v54
	v_add_f32_e32 v54, v50, v54
	v_add_f32_e32 v54, v51, v54
	s_or_b32 s0, s22, 3
	v_add_f32_e32 v54, v52, v54
	s_min_i32 s0, s0, 15
	v_add_f32_e32 v54, v60, v54
	s_add_i32 s0, s0, 1
	v_add_f32_e32 v54, v59, v54
	v_cvt_f32_i32_e32 v55, s0
	v_add_f32_e32 v54, v58, v54
	v_add_f32_e32 v54, v57, v54
	v_add_f32_e32 v54, v56, v54
	v_div_scale_f32 v56, s[0:1], v55, v55, v54
	v_rcp_f32_e32 v61, v56
	v_sub_f32_e32 v53, v53, v29
	v_cvt_pk_bf16_f32 v53, v53, v53
	ds_write_b16 v64, v53 offset:1056
	v_fma_f32 v53, -v56, v61, 1.0
	v_fmac_f32_e32 v61, v53, v61
	v_div_scale_f32 v53, vcc, v54, v55, v54
	v_mul_f32_e32 v62, v53, v61
	v_fma_f32 v63, -v56, v62, v53
	v_fmac_f32_e32 v62, v63, v61
	v_fma_f32 v53, -v56, v62, v53
	v_div_fmas_f32 v53, v53, v61, v62
	v_div_fixup_f32 v53, v53, v55, v54
	v_add_f32_e32 v54, 0, v27
	v_add_f32_e32 v54, v28, v54
	v_add_f32_e32 v54, v29, v54
	v_add_f32_e32 v54, v30, v54
	v_add_f32_e32 v54, v31, v54
	v_add_f32_e32 v54, v46, v54
	v_add_f32_e32 v54, v47, v54
	v_add_f32_e32 v54, v48, v54
	v_add_f32_e32 v54, v49, v54
	v_add_f32_e32 v54, v50, v54
	s_or_b32 s0, s22, 4
	v_add_f32_e32 v54, v51, v54
	s_min_i32 s0, s0, 15
	v_add_f32_e32 v54, v52, v54
	s_add_i32 s0, s0, 1
	v_add_f32_e32 v54, v60, v54
	v_cvt_f32_i32_e32 v55, s0
	v_add_f32_e32 v54, v59, v54
	v_add_f32_e32 v54, v58, v54
	v_add_f32_e32 v54, v57, v54
	v_div_scale_f32 v56, s[0:1], v55, v55, v54
	v_rcp_f32_e32 v57, v56
	v_sub_f32_e32 v53, v53, v28
	v_cvt_pk_bf16_f32 v53, v53, v53
	ds_write_b16 v64, v53 offset:1584
	v_fma_f32 v53, -v56, v57, 1.0
	v_fmac_f32_e32 v57, v53, v57
	v_div_scale_f32 v53, vcc, v54, v55, v54
	v_mul_f32_e32 v61, v53, v57
	v_fma_f32 v62, -v56, v61, v53
	v_fmac_f32_e32 v61, v62, v57
	v_fma_f32 v53, -v56, v61, v53
	v_div_fmas_f32 v53, v53, v57, v61
	v_div_fixup_f32 v53, v53, v55, v54
	v_add_f32_e32 v54, 0, v26
	v_add_f32_e32 v54, v27, v54
	v_add_f32_e32 v54, v28, v54
	v_add_f32_e32 v54, v29, v54
	v_add_f32_e32 v54, v30, v54
	v_add_f32_e32 v54, v31, v54
	v_add_f32_e32 v54, v46, v54
	v_add_f32_e32 v54, v47, v54
	v_add_f32_e32 v54, v48, v54
	v_add_f32_e32 v54, v49, v54
	s_or_b32 s0, s22, 5
	v_add_f32_e32 v54, v50, v54
	s_min_i32 s0, s0, 15
	v_add_f32_e32 v54, v51, v54
	s_add_i32 s0, s0, 1
	v_add_f32_e32 v54, v52, v54
	v_cvt_f32_i32_e32 v55, s0
	v_add_f32_e32 v54, v60, v54
	v_add_f32_e32 v54, v59, v54
	v_add_f32_e32 v54, v58, v54
	v_div_scale_f32 v56, s[0:1], v55, v55, v54
	v_rcp_f32_e32 v57, v56
	v_sub_f32_e32 v53, v53, v27
	v_cvt_pk_bf16_f32 v53, v53, v53
	ds_write_b16 v64, v53 offset:2112
	v_fma_f32 v53, -v56, v57, 1.0
	v_fmac_f32_e32 v57, v53, v57
	v_div_scale_f32 v53, vcc, v54, v55, v54
	v_mul_f32_e32 v58, v53, v57
	v_fma_f32 v61, -v56, v58, v53
	v_fmac_f32_e32 v58, v61, v57
	v_fma_f32 v53, -v56, v58, v53
	v_div_fmas_f32 v53, v53, v57, v58
	v_div_fixup_f32 v53, v53, v55, v54
	v_add_f32_e32 v54, 0, v25
	v_add_f32_e32 v54, v26, v54
	v_add_f32_e32 v54, v27, v54
	v_add_f32_e32 v54, v28, v54
	v_add_f32_e32 v54, v29, v54
	v_add_f32_e32 v54, v30, v54
	v_add_f32_e32 v54, v31, v54
	v_add_f32_e32 v54, v46, v54
	v_add_f32_e32 v54, v47, v54
	v_add_f32_e32 v54, v48, v54
	s_or_b32 s0, s22, 6
	v_add_f32_e32 v54, v49, v54
	s_min_i32 s0, s0, 15
	v_add_f32_e32 v54, v50, v54
	s_add_i32 s0, s0, 1
	v_add_f32_e32 v54, v51, v54
	v_cvt_f32_i32_e32 v55, s0
	v_add_f32_e32 v54, v52, v54
	v_add_f32_e32 v54, v60, v54
	v_add_f32_e32 v54, v59, v54
	v_div_scale_f32 v56, s[0:1], v55, v55, v54
	v_rcp_f32_e32 v57, v56
	v_sub_f32_e32 v53, v53, v26
	v_cvt_pk_bf16_f32 v53, v53, v53
	ds_write_b16 v64, v53 offset:2640
	v_fma_f32 v53, -v56, v57, 1.0
	v_fmac_f32_e32 v57, v53, v57
	v_div_scale_f32 v53, vcc, v54, v55, v54
	v_mul_f32_e32 v58, v53, v57
	v_fma_f32 v59, -v56, v58, v53
	v_fmac_f32_e32 v58, v59, v57
	v_fma_f32 v53, -v56, v58, v53
	v_div_fmas_f32 v53, v53, v57, v58
	v_div_fixup_f32 v53, v53, v55, v54
	v_add_f32_e32 v54, 0, v24
	v_add_f32_e32 v54, v25, v54
	v_add_f32_e32 v54, v26, v54
	v_add_f32_e32 v54, v27, v54
	v_add_f32_e32 v54, v28, v54
	v_add_f32_e32 v54, v29, v54
	v_add_f32_e32 v54, v30, v54
	v_add_f32_e32 v54, v31, v54
	v_add_f32_e32 v54, v46, v54
	v_add_f32_e32 v54, v47, v54
	s_or_b32 s0, s22, 7
	v_add_f32_e32 v54, v48, v54
	s_min_i32 s0, s0, 15
	v_add_f32_e32 v54, v49, v54
	s_add_i32 s0, s0, 1
	v_add_f32_e32 v54, v50, v54
	v_cvt_f32_i32_e32 v55, s0
	v_add_f32_e32 v54, v51, v54
	v_add_f32_e32 v54, v52, v54
	v_add_f32_e32 v54, v60, v54
	v_div_scale_f32 v56, s[0:1], v55, v55, v54
	v_rcp_f32_e32 v57, v56
	v_sub_f32_e32 v53, v53, v25
	v_readlane_b32 s0, v253, 40
	v_cvt_pk_bf16_f32 v53, v53, v53
	s_nop 1
	v_add_u32_e32 v58, s0, v43
	ds_write_b16 v58, v53
	v_fma_f32 v53, -v56, v57, 1.0
	v_fmac_f32_e32 v57, v53, v57
	v_div_scale_f32 v53, vcc, v54, v55, v54
	v_mul_f32_e32 v59, v53, v57
	v_fma_f32 v60, -v56, v59, v53
	v_fmac_f32_e32 v59, v60, v57
	v_fma_f32 v53, -v56, v59, v53
	v_div_fmas_f32 v53, v53, v57, v59
	v_div_fixup_f32 v53, v53, v55, v54
	v_add_f32_e32 v54, 0, v23
	v_add_f32_e32 v54, v24, v54
	v_add_f32_e32 v54, v25, v54
	v_add_f32_e32 v54, v26, v54
	v_add_f32_e32 v54, v27, v54
	v_add_f32_e32 v54, v28, v54
	v_add_f32_e32 v54, v29, v54
	v_add_f32_e32 v54, v30, v54
	v_add_f32_e32 v54, v31, v54
	v_add_f32_e32 v54, v46, v54
	s_or_b32 s0, s22, 8
	v_add_f32_e32 v54, v47, v54
	s_min_i32 s0, s0, 15
	v_add_f32_e32 v54, v48, v54
	s_add_i32 s0, s0, 1
	v_add_f32_e32 v54, v49, v54
	v_cvt_f32_i32_e32 v55, s0
	v_add_f32_e32 v54, v50, v54
	v_add_f32_e32 v54, v51, v54
	v_add_f32_e32 v54, v52, v54
	v_div_scale_f32 v56, s[0:1], v55, v55, v54
	v_rcp_f32_e32 v57, v56
	v_sub_f32_e32 v53, v53, v24
	v_cvt_pk_bf16_f32 v53, v53, v53
	ds_write_b16 v58, v53 offset:528
	v_fma_f32 v53, -v56, v57, 1.0
	v_fmac_f32_e32 v57, v53, v57
	v_div_scale_f32 v53, vcc, v54, v55, v54
	v_mul_f32_e32 v59, v53, v57
	v_fma_f32 v60, -v56, v59, v53
	v_fmac_f32_e32 v59, v60, v57
	v_fma_f32 v53, -v56, v59, v53
	v_div_fmas_f32 v53, v53, v57, v59
	v_div_fixup_f32 v53, v53, v55, v54
	v_add_f32_e32 v54, 0, v22
	v_add_f32_e32 v54, v23, v54
	v_add_f32_e32 v54, v24, v54
	v_add_f32_e32 v54, v25, v54
	v_add_f32_e32 v54, v26, v54
	v_add_f32_e32 v54, v27, v54
	v_add_f32_e32 v54, v28, v54
	v_add_f32_e32 v54, v29, v54
	v_add_f32_e32 v54, v30, v54
	v_add_f32_e32 v54, v31, v54
	s_or_b32 s0, s22, 9
	v_add_f32_e32 v54, v46, v54
	s_min_i32 s0, s0, 15
	v_add_f32_e32 v54, v47, v54
	s_add_i32 s0, s0, 1
	v_add_f32_e32 v54, v48, v54
	v_cvt_f32_i32_e32 v55, s0
	v_add_f32_e32 v54, v49, v54
	v_add_f32_e32 v54, v50, v54
	v_add_f32_e32 v54, v51, v54
	v_div_scale_f32 v56, s[0:1], v55, v55, v54
	v_rcp_f32_e32 v57, v56
	v_sub_f32_e32 v53, v53, v23
	v_cvt_pk_bf16_f32 v53, v53, v53
	ds_write_b16 v58, v53 offset:1056
	v_fma_f32 v53, -v56, v57, 1.0
	v_fmac_f32_e32 v57, v53, v57
	v_div_scale_f32 v53, vcc, v54, v55, v54
	v_mul_f32_e32 v59, v53, v57
	v_fma_f32 v60, -v56, v59, v53
	v_fmac_f32_e32 v59, v60, v57
	v_fma_f32 v53, -v56, v59, v53
	v_div_fmas_f32 v53, v53, v57, v59
	v_div_fixup_f32 v53, v53, v55, v54
	v_add_f32_e32 v54, 0, v21
	v_add_f32_e32 v54, v22, v54
	v_add_f32_e32 v54, v23, v54
	v_add_f32_e32 v54, v24, v54
	v_add_f32_e32 v54, v25, v54
	v_add_f32_e32 v54, v26, v54
	v_add_f32_e32 v54, v27, v54
	v_add_f32_e32 v54, v28, v54
	v_add_f32_e32 v54, v29, v54
	v_add_f32_e32 v54, v30, v54
	s_or_b32 s0, s22, 10
	v_add_f32_e32 v54, v31, v54
	s_min_i32 s0, s0, 15
	v_add_f32_e32 v54, v46, v54
	s_add_i32 s0, s0, 1
	v_add_f32_e32 v54, v47, v54
	v_cvt_f32_i32_e32 v55, s0
	v_add_f32_e32 v54, v48, v54
	v_add_f32_e32 v54, v49, v54
	v_add_f32_e32 v54, v50, v54
	v_div_scale_f32 v56, s[0:1], v55, v55, v54
	v_rcp_f32_e32 v57, v56
	v_sub_f32_e32 v53, v53, v22
	v_cvt_pk_bf16_f32 v53, v53, v53
	ds_write_b16 v58, v53 offset:1584
	v_fma_f32 v53, -v56, v57, 1.0
	v_fmac_f32_e32 v57, v53, v57
	v_div_scale_f32 v53, vcc, v54, v55, v54
	v_mul_f32_e32 v59, v53, v57
	v_fma_f32 v60, -v56, v59, v53
	v_fmac_f32_e32 v59, v60, v57
	v_fma_f32 v53, -v56, v59, v53
	v_div_fmas_f32 v53, v53, v57, v59
	v_div_fixup_f32 v53, v53, v55, v54
	v_add_f32_e32 v54, 0, v20
	v_add_f32_e32 v54, v21, v54
	v_add_f32_e32 v54, v22, v54
	v_add_f32_e32 v54, v23, v54
	v_add_f32_e32 v54, v24, v54
	v_add_f32_e32 v54, v25, v54
	v_add_f32_e32 v54, v26, v54
	v_add_f32_e32 v54, v27, v54
	v_add_f32_e32 v54, v28, v54
	v_add_f32_e32 v54, v29, v54
	s_or_b32 s0, s22, 11
	v_add_f32_e32 v54, v30, v54
	s_min_i32 s0, s0, 15
	v_add_f32_e32 v54, v31, v54
	s_add_i32 s0, s0, 1
	v_add_f32_e32 v54, v46, v54
	v_cvt_f32_i32_e32 v55, s0
	v_add_f32_e32 v54, v47, v54
	v_add_f32_e32 v54, v48, v54
	v_add_f32_e32 v54, v49, v54
	v_div_scale_f32 v56, s[0:1], v55, v55, v54
	v_rcp_f32_e32 v57, v56
	v_sub_f32_e32 v53, v53, v21
	v_cvt_pk_bf16_f32 v53, v53, v53
	ds_write_b16 v58, v53 offset:2112
	v_fma_f32 v53, -v56, v57, 1.0
	v_fmac_f32_e32 v57, v53, v57
	v_div_scale_f32 v53, vcc, v54, v55, v54
	v_mul_f32_e32 v59, v53, v57
	v_fma_f32 v60, -v56, v59, v53
	v_fmac_f32_e32 v59, v60, v57
	v_fma_f32 v53, -v56, v59, v53
	v_div_fmas_f32 v53, v53, v57, v59
	v_div_fixup_f32 v53, v53, v55, v54
	v_add_f32_e32 v54, 0, v19
	v_add_f32_e32 v54, v20, v54
	v_add_f32_e32 v54, v21, v54
	v_add_f32_e32 v54, v22, v54
	v_add_f32_e32 v54, v23, v54
	v_add_f32_e32 v54, v24, v54
	v_add_f32_e32 v54, v25, v54
	v_add_f32_e32 v54, v26, v54
	v_add_f32_e32 v54, v27, v54
	v_add_f32_e32 v54, v28, v54
	v_add_f32_e32 v54, v29, v54
	s_min_i32 s0, s24, 15
	v_add_f32_e32 v54, v30, v54
	s_add_i32 s0, s0, 1
	v_add_f32_e32 v54, v31, v54
	v_cvt_f32_i32_e32 v55, s0
	v_add_f32_e32 v54, v46, v54
	v_add_f32_e32 v54, v47, v54
	v_add_f32_e32 v54, v48, v54
	v_div_scale_f32 v56, s[0:1], v55, v55, v54
	v_rcp_f32_e32 v57, v56
	v_sub_f32_e32 v53, v53, v20
	v_cvt_pk_bf16_f32 v53, v53, v53
	ds_write_b16 v58, v53 offset:2640
	v_fma_f32 v53, -v56, v57, 1.0
	v_fmac_f32_e32 v57, v53, v57
	v_div_scale_f32 v53, vcc, v54, v55, v54
	v_mul_f32_e32 v58, v53, v57
	v_fma_f32 v59, -v56, v58, v53
	v_fmac_f32_e32 v58, v59, v57
	v_fma_f32 v53, -v56, v58, v53
	v_div_fmas_f32 v53, v53, v57, v58
	v_div_fixup_f32 v53, v53, v55, v54
	v_add_f32_e32 v54, 0, v18
	v_add_f32_e32 v54, v19, v54
	v_add_f32_e32 v54, v20, v54
	v_add_f32_e32 v54, v21, v54
	v_add_f32_e32 v54, v22, v54
	v_add_f32_e32 v54, v23, v54
	v_add_f32_e32 v54, v24, v54
	v_add_f32_e32 v54, v25, v54
	v_add_f32_e32 v54, v26, v54
	v_add_f32_e32 v54, v27, v54
	s_or_b32 s0, s22, 13
	v_add_f32_e32 v54, v28, v54
	s_min_i32 s0, s0, 15
	v_add_f32_e32 v54, v29, v54
	s_add_i32 s0, s0, 1
	v_add_f32_e32 v54, v30, v54
	v_cvt_f32_i32_e32 v55, s0
	v_add_f32_e32 v54, v31, v54
	v_add_f32_e32 v54, v46, v54
	v_add_f32_e32 v54, v47, v54
	v_div_scale_f32 v56, s[0:1], v55, v55, v54
	v_rcp_f32_e32 v57, v56
	v_sub_f32_e32 v53, v53, v19
	v_readlane_b32 s0, v253, 42
	v_cvt_pk_bf16_f32 v53, v53, v53
	s_nop 1
	v_add_u32_e32 v58, s0, v43
	ds_write_b16 v58, v53
	v_fma_f32 v53, -v56, v57, 1.0
	v_fmac_f32_e32 v57, v53, v57
	v_div_scale_f32 v53, vcc, v54, v55, v54
	v_mul_f32_e32 v59, v53, v57
	v_fma_f32 v60, -v56, v59, v53
	v_fmac_f32_e32 v59, v60, v57
	v_fma_f32 v53, -v56, v59, v53
	v_div_fmas_f32 v53, v53, v57, v59
	v_div_fixup_f32 v53, v53, v55, v54
	v_add_f32_e32 v54, 0, v17
	v_add_f32_e32 v54, v18, v54
	v_add_f32_e32 v54, v19, v54
	v_add_f32_e32 v54, v20, v54
	v_add_f32_e32 v54, v21, v54
	v_add_f32_e32 v54, v22, v54
	v_add_f32_e32 v54, v23, v54
	v_add_f32_e32 v54, v24, v54
	v_add_f32_e32 v54, v25, v54
	v_add_f32_e32 v54, v26, v54
	s_or_b32 s0, s22, 14
	v_add_f32_e32 v54, v27, v54
	s_min_i32 s0, s0, 15
	v_add_f32_e32 v54, v28, v54
	s_add_i32 s0, s0, 1
	v_add_f32_e32 v54, v29, v54
	v_cvt_f32_i32_e32 v55, s0
	v_add_f32_e32 v54, v30, v54
	v_add_f32_e32 v54, v31, v54
	v_add_f32_e32 v54, v46, v54
	v_div_scale_f32 v56, s[0:1], v55, v55, v54
	v_rcp_f32_e32 v57, v56
	v_sub_f32_e32 v53, v53, v18
	v_cvt_pk_bf16_f32 v53, v53, v53
	ds_write_b16 v58, v53 offset:528
	v_fma_f32 v53, -v56, v57, 1.0
	v_fmac_f32_e32 v57, v53, v57
	v_div_scale_f32 v53, vcc, v54, v55, v54
	v_mul_f32_e32 v59, v53, v57
	v_fma_f32 v60, -v56, v59, v53
	v_fmac_f32_e32 v59, v60, v57
	v_fma_f32 v53, -v56, v59, v53
	v_div_fmas_f32 v53, v53, v57, v59
	v_div_fixup_f32 v53, v53, v55, v54
	v_add_f32_e32 v54, 0, v16
	v_add_f32_e32 v54, v17, v54
	v_add_f32_e32 v54, v18, v54
	v_add_f32_e32 v54, v19, v54
	v_add_f32_e32 v54, v20, v54
	v_add_f32_e32 v54, v21, v54
	v_add_f32_e32 v54, v22, v54
	v_add_f32_e32 v54, v23, v54
	v_add_f32_e32 v54, v24, v54
	v_add_f32_e32 v54, v25, v54
	s_or_b32 s0, s22, 15
	v_add_f32_e32 v54, v26, v54
	s_min_i32 s0, s0, 15
	v_add_f32_e32 v54, v27, v54
	s_add_i32 s0, s0, 1
	v_add_f32_e32 v54, v28, v54
	v_cvt_f32_i32_e32 v55, s0
	v_add_f32_e32 v54, v29, v54
	v_add_f32_e32 v54, v30, v54
	v_add_f32_e32 v54, v31, v54
	v_div_scale_f32 v56, s[0:1], v55, v55, v54
	v_rcp_f32_e32 v57, v56
	v_sub_f32_e32 v53, v53, v17
	v_cvt_pk_bf16_f32 v53, v53, v53
	ds_write_b16 v58, v53 offset:1056
	v_fma_f32 v53, -v56, v57, 1.0
	v_fmac_f32_e32 v57, v53, v57
	v_div_scale_f32 v53, vcc, v54, v55, v54
	v_mul_f32_e32 v59, v53, v57
	v_fma_f32 v60, -v56, v59, v53
	v_fmac_f32_e32 v59, v60, v57
	v_fma_f32 v53, -v56, v59, v53
	v_div_fmas_f32 v53, v53, v57, v59
	v_div_fixup_f32 v53, v53, v55, v54
	v_add_f32_e32 v54, 0, v15
	v_add_f32_e32 v54, v16, v54
	v_add_f32_e32 v54, v17, v54
	v_add_f32_e32 v54, v18, v54
	v_add_f32_e32 v54, v19, v54
	v_add_f32_e32 v54, v20, v54
	v_add_f32_e32 v54, v21, v54
	v_add_f32_e32 v54, v22, v54
	v_add_f32_e32 v54, v23, v54
	v_add_f32_e32 v54, v24, v54
	s_or_b32 s0, s22, 16
	v_add_f32_e32 v54, v25, v54
	s_min_i32 s0, s0, 15
	v_add_f32_e32 v54, v26, v54
	s_add_i32 s0, s0, 1
	v_add_f32_e32 v54, v27, v54
	v_cvt_f32_i32_e32 v55, s0
	v_add_f32_e32 v54, v28, v54
	v_add_f32_e32 v54, v29, v54
	v_add_f32_e32 v54, v30, v54
	v_div_scale_f32 v56, s[0:1], v55, v55, v54
	v_rcp_f32_e32 v57, v56
	v_sub_f32_e32 v53, v53, v16
	v_cvt_pk_bf16_f32 v53, v53, v53
	ds_write_b16 v58, v53 offset:1584
	v_fma_f32 v53, -v56, v57, 1.0
	v_fmac_f32_e32 v57, v53, v57
	v_div_scale_f32 v53, vcc, v54, v55, v54
	v_mul_f32_e32 v59, v53, v57
	v_fma_f32 v60, -v56, v59, v53
	v_fmac_f32_e32 v59, v60, v57
	v_fma_f32 v53, -v56, v59, v53
	v_div_fmas_f32 v53, v53, v57, v59
	v_div_fixup_f32 v53, v53, v55, v54
	v_add_f32_e32 v54, 0, v14
	v_add_f32_e32 v54, v15, v54
	v_add_f32_e32 v54, v16, v54
	v_add_f32_e32 v54, v17, v54
	v_add_f32_e32 v54, v18, v54
	v_add_f32_e32 v54, v19, v54
	v_add_f32_e32 v54, v20, v54
	v_add_f32_e32 v54, v21, v54
	v_add_f32_e32 v54, v22, v54
	v_add_f32_e32 v54, v23, v54
	s_or_b32 s0, s22, 17
	v_add_f32_e32 v54, v24, v54
	s_min_i32 s0, s0, 15
; #define POOL_WIN(WIN) do { _Pragma("unroll") for (int t = 0; t < 32; ++t) { float s = 0.f; _Pragma("unroll") for (int j = 0; j < WIN; ++j) s += x[15 + t - j]; \
;             const int pos = pos0 + ts + t; const float cnt = (float)(pos + 1 < WIN ? pos + 1 : WIN); pl[(ts + t) * PS + c] = f2bf(s / cnt - x[15 + t]); } } while (0)
; __device__ __forceinline__ void pool_item(int l, int it, LAS unsigned char* lds, const bf16_t* PLB, bf16_t* YC, const float* pool_w, const float* pool_scale, int tid, int lane, int wave) {
;     ...
;         if (g == 0) POOL_WIN(2); else if (g == 1) POOL_WIN(4); else if (g == 2) POOL_WIN(8); else POOL_WIN(16);
	v_add_f32_e32 v54, v25, v54
	s_add_i32 s0, s0, 1
	v_add_f32_e32 v54, v26, v54
	v_cvt_f32_i32_e32 v55, s0
	v_add_f32_e32 v54, v27, v54
	v_add_f32_e32 v54, v28, v54
	v_add_f32_e32 v54, v29, v54
	v_div_scale_f32 v56, s[0:1], v55, v55, v54
	v_rcp_f32_e32 v57, v56
	v_sub_f32_e32 v53, v53, v15
	v_cvt_pk_bf16_f32 v53, v53, v53
	ds_write_b16 v58, v53 offset:2112
	v_fma_f32 v53, -v56, v57, 1.0
	v_fmac_f32_e32 v57, v53, v57
	v_div_scale_f32 v53, vcc, v54, v55, v54
	v_mul_f32_e32 v59, v53, v57
	v_fma_f32 v60, -v56, v59, v53
	v_fmac_f32_e32 v59, v60, v57
	v_fma_f32 v53, -v56, v59, v53
	v_div_fmas_f32 v53, v53, v57, v59
	v_div_fixup_f32 v53, v53, v55, v54
	v_add_f32_e32 v54, 0, v13
	v_add_f32_e32 v54, v14, v54
	v_add_f32_e32 v54, v15, v54
	v_add_f32_e32 v54, v16, v54
	v_add_f32_e32 v54, v17, v54
	v_add_f32_e32 v54, v18, v54
	v_add_f32_e32 v54, v19, v54
	v_add_f32_e32 v54, v20, v54
	v_add_f32_e32 v54, v21, v54
	v_add_f32_e32 v54, v22, v54
	s_or_b32 s0, s22, 18
	v_add_f32_e32 v54, v23, v54
	s_min_i32 s0, s0, 15
	v_add_f32_e32 v54, v24, v54
	s_add_i32 s0, s0, 1
	v_add_f32_e32 v54, v25, v54
	v_cvt_f32_i32_e32 v55, s0
	v_add_f32_e32 v54, v26, v54
	v_add_f32_e32 v54, v27, v54
	v_add_f32_e32 v54, v28, v54
	v_div_scale_f32 v56, s[0:1], v55, v55, v54
	v_rcp_f32_e32 v57, v56
	v_sub_f32_e32 v53, v53, v14
	v_cvt_pk_bf16_f32 v53, v53, v53
	ds_write_b16 v58, v53 offset:2640
	v_fma_f32 v53, -v56, v57, 1.0
	v_fmac_f32_e32 v57, v53, v57
	v_div_scale_f32 v53, vcc, v54, v55, v54
	v_mul_f32_e32 v59, v53, v57
	v_fma_f32 v60, -v56, v59, v53
	v_fmac_f32_e32 v59, v60, v57
	v_fma_f32 v53, -v56, v59, v53
	v_div_fmas_f32 v53, v53, v57, v59
	v_div_fixup_f32 v53, v53, v55, v54
	v_add_f32_e32 v54, 0, v12
	v_add_f32_e32 v54, v13, v54
	v_add_f32_e32 v54, v14, v54
	v_add_f32_e32 v54, v15, v54
	v_add_f32_e32 v54, v16, v54
	v_add_f32_e32 v54, v17, v54
	v_add_f32_e32 v54, v18, v54
	v_add_f32_e32 v54, v19, v54
	v_add_f32_e32 v54, v20, v54
	v_add_f32_e32 v54, v21, v54
	s_or_b32 s0, s22, 19
	v_add_f32_e32 v54, v22, v54
	s_min_i32 s0, s0, 15
	v_add_f32_e32 v54, v23, v54
	s_add_i32 s0, s0, 1
	v_add_f32_e32 v54, v24, v54
	v_cvt_f32_i32_e32 v55, s0
	v_add_f32_e32 v54, v25, v54
	v_add_f32_e32 v54, v26, v54
	v_add_f32_e32 v54, v27, v54
	v_div_scale_f32 v56, s[0:1], v55, v55, v54
	v_rcp_f32_e32 v57, v56
	v_sub_f32_e32 v53, v53, v13
	v_cvt_pk_bf16_f32 v53, v53, v53
	ds_write_b16 v58, v53 offset:3168
	v_fma_f32 v53, -v56, v57, 1.0
	v_fmac_f32_e32 v57, v53, v57
	v_div_scale_f32 v53, vcc, v54, v55, v54
	v_mul_f32_e32 v59, v53, v57
	v_fma_f32 v60, -v56, v59, v53
	v_fmac_f32_e32 v59, v60, v57
	v_fma_f32 v53, -v56, v59, v53
	v_div_fmas_f32 v53, v53, v57, v59
	v_div_fixup_f32 v53, v53, v55, v54
	v_add_f32_e32 v54, 0, v11
	v_add_f32_e32 v54, v12, v54
	v_add_f32_e32 v54, v13, v54
	v_add_f32_e32 v54, v14, v54
	v_add_f32_e32 v54, v15, v54
	v_add_f32_e32 v54, v16, v54
	v_add_f32_e32 v54, v17, v54
	v_add_f32_e32 v54, v18, v54
	v_add_f32_e32 v54, v19, v54
	v_add_f32_e32 v54, v20, v54
	s_or_b32 s0, s22, 20
	v_add_f32_e32 v54, v21, v54
	s_min_i32 s0, s0, 15
	v_add_f32_e32 v54, v22, v54
	s_add_i32 s0, s0, 1
	v_add_f32_e32 v54, v23, v54
	v_cvt_f32_i32_e32 v55, s0
	v_add_f32_e32 v54, v24, v54
	v_add_f32_e32 v54, v25, v54
	v_add_f32_e32 v54, v26, v54
	v_div_scale_f32 v56, s[0:1], v55, v55, v54
	v_rcp_f32_e32 v57, v56
	v_sub_f32_e32 v53, v53, v12
	v_cvt_pk_bf16_f32 v53, v53, v53
	ds_write_b16 v58, v53 offset:3696
	v_fma_f32 v53, -v56, v57, 1.0
	v_fmac_f32_e32 v57, v53, v57
	v_div_scale_f32 v53, vcc, v54, v55, v54
	v_mul_f32_e32 v59, v53, v57
	v_fma_f32 v60, -v56, v59, v53
	v_fmac_f32_e32 v59, v60, v57
	v_fma_f32 v53, -v56, v59, v53
	v_div_fmas_f32 v53, v53, v57, v59
	v_div_fixup_f32 v53, v53, v55, v54
	v_add_f32_e32 v54, 0, v10
	v_add_f32_e32 v54, v11, v54
	v_add_f32_e32 v54, v12, v54
	v_add_f32_e32 v54, v13, v54
	v_add_f32_e32 v54, v14, v54
	v_add_f32_e32 v54, v15, v54
	v_add_f32_e32 v54, v16, v54
	v_add_f32_e32 v54, v17, v54
	v_add_f32_e32 v54, v18, v54
	v_add_f32_e32 v54, v19, v54
	s_or_b32 s0, s22, 21
	v_add_f32_e32 v54, v20, v54
	s_min_i32 s0, s0, 15
	v_add_f32_e32 v54, v21, v54
	s_add_i32 s0, s0, 1
	v_add_f32_e32 v54, v22, v54
	v_cvt_f32_i32_e32 v55, s0
	v_add_f32_e32 v54, v23, v54
	v_add_f32_e32 v54, v24, v54
	v_add_f32_e32 v54, v25, v54
	v_div_scale_f32 v56, s[0:1], v55, v55, v54
	v_rcp_f32_e32 v57, v56
	v_sub_f32_e32 v53, v53, v11
	v_cvt_pk_bf16_f32 v53, v53, v53
	ds_write_b16 v58, v53 offset:4224
	v_fma_f32 v53, -v56, v57, 1.0
	v_fmac_f32_e32 v57, v53, v57
	v_div_scale_f32 v53, vcc, v54, v55, v54
	v_mul_f32_e32 v59, v53, v57
	v_fma_f32 v60, -v56, v59, v53
	v_fmac_f32_e32 v59, v60, v57
	v_fma_f32 v53, -v56, v59, v53
	v_div_fmas_f32 v53, v53, v57, v59
	v_div_fixup_f32 v53, v53, v55, v54
	v_add_f32_e32 v54, 0, v9
	v_add_f32_e32 v54, v10, v54
	v_add_f32_e32 v54, v11, v54
	v_add_f32_e32 v54, v12, v54
	v_add_f32_e32 v54, v13, v54
	v_add_f32_e32 v54, v14, v54
	v_add_f32_e32 v54, v15, v54
	v_add_f32_e32 v54, v16, v54
	v_add_f32_e32 v54, v17, v54
	v_add_f32_e32 v54, v18, v54
	s_or_b32 s0, s22, 22
	v_add_f32_e32 v54, v19, v54
	s_min_i32 s0, s0, 15
	v_add_f32_e32 v54, v20, v54
	s_add_i32 s0, s0, 1
	v_add_f32_e32 v54, v21, v54
	v_cvt_f32_i32_e32 v55, s0
	v_add_f32_e32 v54, v22, v54
	v_add_f32_e32 v54, v23, v54
	v_add_f32_e32 v54, v24, v54
	v_div_scale_f32 v56, s[0:1], v55, v55, v54
	v_rcp_f32_e32 v57, v56
	v_sub_f32_e32 v53, v53, v10
	v_cvt_pk_bf16_f32 v53, v53, v53
	ds_write_b16 v58, v53 offset:4752
	v_fma_f32 v53, -v56, v57, 1.0
	v_fmac_f32_e32 v57, v53, v57
	v_div_scale_f32 v53, vcc, v54, v55, v54
	v_mul_f32_e32 v59, v53, v57
	v_fma_f32 v60, -v56, v59, v53
	v_fmac_f32_e32 v59, v60, v57
	v_fma_f32 v53, -v56, v59, v53
; #define POOL_WIN(WIN) do { _Pragma("unroll") for (int t = 0; t < 32; ++t) { float s = 0.f; _Pragma("unroll") for (int j = 0; j < WIN; ++j) s += x[15 + t - j]; \
;             const int pos = pos0 + ts + t; const float cnt = (float)(pos + 1 < WIN ? pos + 1 : WIN); pl[(ts + t) * PS + c] = f2bf(s / cnt - x[15 + t]); } } while (0)
; __device__ __forceinline__ void pool_item(int l, int it, LAS unsigned char* lds, const bf16_t* PLB, bf16_t* YC, const float* pool_w, const float* pool_scale, int tid, int lane, int wave) {
;     ...
;         if (g == 0) POOL_WIN(2); else if (g == 1) POOL_WIN(4); else if (g == 2) POOL_WIN(8); else POOL_WIN(16);
	v_div_fmas_f32 v53, v53, v57, v59
	v_div_fixup_f32 v53, v53, v55, v54
	v_add_f32_e32 v54, 0, v8
	v_add_f32_e32 v54, v9, v54
	v_add_f32_e32 v54, v10, v54
	v_add_f32_e32 v54, v11, v54
	v_add_f32_e32 v54, v12, v54
	v_add_f32_e32 v54, v13, v54
	v_add_f32_e32 v54, v14, v54
	v_add_f32_e32 v54, v15, v54
	v_add_f32_e32 v54, v16, v54
	v_add_f32_e32 v54, v17, v54
	s_or_b32 s0, s22, 23
	v_add_f32_e32 v54, v18, v54
	s_min_i32 s0, s0, 15
	v_add_f32_e32 v54, v19, v54
	s_add_i32 s0, s0, 1
	v_add_f32_e32 v54, v20, v54
	v_cvt_f32_i32_e32 v55, s0
	v_add_f32_e32 v54, v21, v54
	v_add_f32_e32 v54, v22, v54
	v_add_f32_e32 v54, v23, v54
	v_div_scale_f32 v56, s[0:1], v55, v55, v54
	v_rcp_f32_e32 v57, v56
	v_sub_f32_e32 v53, v53, v9
	v_cvt_pk_bf16_f32 v53, v53, v53
	ds_write_b16 v58, v53 offset:5280
	v_fma_f32 v53, -v56, v57, 1.0
	v_fmac_f32_e32 v57, v53, v57
	v_div_scale_f32 v53, vcc, v54, v55, v54
	v_mul_f32_e32 v59, v53, v57
	v_fma_f32 v60, -v56, v59, v53
	v_fmac_f32_e32 v59, v60, v57
	v_fma_f32 v53, -v56, v59, v53
	v_div_fmas_f32 v53, v53, v57, v59
	v_div_fixup_f32 v53, v53, v55, v54
	v_add_f32_e32 v54, 0, v7
	v_add_f32_e32 v54, v8, v54
	v_add_f32_e32 v54, v9, v54
	v_add_f32_e32 v54, v10, v54
	v_add_f32_e32 v54, v11, v54
	v_add_f32_e32 v54, v12, v54
	v_add_f32_e32 v54, v13, v54
	v_add_f32_e32 v54, v14, v54
	v_add_f32_e32 v54, v15, v54
	v_add_f32_e32 v54, v16, v54
	v_add_f32_e32 v54, v17, v54
	s_min_i32 s0, s23, 15
	v_add_f32_e32 v54, v18, v54
	s_add_i32 s0, s0, 1
	v_add_f32_e32 v54, v19, v54
	v_cvt_f32_i32_e32 v55, s0
	v_add_f32_e32 v54, v20, v54
	v_add_f32_e32 v54, v21, v54
	v_add_f32_e32 v54, v22, v54
	v_div_scale_f32 v56, s[0:1], v55, v55, v54
	v_rcp_f32_e32 v57, v56
	v_sub_f32_e32 v53, v53, v8
	v_cvt_pk_bf16_f32 v53, v53, v53
	ds_write_b16 v58, v53 offset:5808
	v_fma_f32 v53, -v56, v57, 1.0
	v_fmac_f32_e32 v57, v53, v57
	v_div_scale_f32 v53, vcc, v54, v55, v54
	v_mul_f32_e32 v58, v53, v57
	v_fma_f32 v59, -v56, v58, v53
	v_fmac_f32_e32 v58, v59, v57
	v_fma_f32 v53, -v56, v58, v53
	v_div_fmas_f32 v53, v53, v57, v58
	v_div_fixup_f32 v53, v53, v55, v54
	v_add_f32_e32 v54, 0, v6
	v_add_f32_e32 v54, v7, v54
	v_add_f32_e32 v54, v8, v54
	v_add_f32_e32 v54, v9, v54
	v_add_f32_e32 v54, v10, v54
	v_add_f32_e32 v54, v11, v54
	v_add_f32_e32 v54, v12, v54
	v_add_f32_e32 v54, v13, v54
	v_add_f32_e32 v54, v14, v54
	v_add_f32_e32 v54, v15, v54
	s_or_b32 s0, s22, 25
	v_add_f32_e32 v54, v16, v54
	s_min_i32 s0, s0, 15
	v_add_f32_e32 v54, v17, v54
	s_add_i32 s0, s0, 1
	v_add_f32_e32 v54, v18, v54
	v_cvt_f32_i32_e32 v55, s0
	v_add_f32_e32 v54, v19, v54
	v_add_f32_e32 v54, v20, v54
	v_add_f32_e32 v54, v21, v54
	v_div_scale_f32 v56, s[0:1], v55, v55, v54
	v_rcp_f32_e32 v57, v56
	v_sub_f32_e32 v53, v53, v7
	v_readlane_b32 s0, v255, 62
	v_cvt_pk_bf16_f32 v53, v53, v53
	s_nop 1
	v_add_u32_e32 v58, s0, v43
	ds_write_b16 v58, v53
	v_fma_f32 v53, -v56, v57, 1.0
	v_fmac_f32_e32 v57, v53, v57
	v_div_scale_f32 v53, vcc, v54, v55, v54
	v_mul_f32_e32 v58, v53, v57
	v_fma_f32 v59, -v56, v58, v53
	v_fmac_f32_e32 v58, v59, v57
	v_fma_f32 v53, -v56, v58, v53
	v_div_fmas_f32 v53, v53, v57, v58
	v_div_fixup_f32 v53, v53, v55, v54
	v_add_f32_e32 v54, 0, v5
	v_add_f32_e32 v54, v6, v54
	v_add_f32_e32 v54, v7, v54
	v_add_f32_e32 v54, v8, v54
	v_add_f32_e32 v54, v9, v54
	v_add_f32_e32 v54, v10, v54
	v_add_f32_e32 v54, v11, v54
	v_add_f32_e32 v54, v12, v54
	v_add_f32_e32 v54, v13, v54
	v_add_f32_e32 v54, v14, v54
	s_or_b32 s0, s22, 26
	v_add_f32_e32 v54, v15, v54
	s_min_i32 s0, s0, 15
	v_add_f32_e32 v54, v16, v54
	s_add_i32 s0, s0, 1
	v_add_f32_e32 v54, v17, v54
	v_cvt_f32_i32_e32 v55, s0
	v_add_f32_e32 v54, v18, v54
	v_add_f32_e32 v54, v19, v54
	v_add_f32_e32 v54, v20, v54
	v_div_scale_f32 v56, s[0:1], v55, v55, v54
	v_rcp_f32_e32 v57, v56
	v_sub_f32_e32 v53, v53, v6
	v_readlane_b32 s0, v254, 1
	v_cvt_pk_bf16_f32 v53, v53, v53
	s_nop 1
	v_add_u32_e32 v58, s0, v43
	ds_write_b16 v58, v53
	v_fma_f32 v53, -v56, v57, 1.0
	v_fmac_f32_e32 v57, v53, v57
	v_div_scale_f32 v53, vcc, v54, v55, v54
	v_mul_f32_e32 v58, v53, v57
	v_fma_f32 v59, -v56, v58, v53
	v_fmac_f32_e32 v58, v59, v57
	v_fma_f32 v53, -v56, v58, v53
	v_div_fmas_f32 v53, v53, v57, v58
	v_div_fixup_f32 v53, v53, v55, v54
	v_add_f32_e32 v54, 0, v4
	v_add_f32_e32 v54, v5, v54
	v_add_f32_e32 v54, v6, v54
	v_add_f32_e32 v54, v7, v54
	v_add_f32_e32 v54, v8, v54
	v_add_f32_e32 v54, v9, v54
	v_add_f32_e32 v54, v10, v54
	v_add_f32_e32 v54, v11, v54
	v_add_f32_e32 v54, v12, v54
	v_add_f32_e32 v54, v13, v54
	s_or_b32 s0, s22, 27
	v_add_f32_e32 v54, v14, v54
	s_min_i32 s0, s0, 15
	v_add_f32_e32 v54, v15, v54
	s_add_i32 s0, s0, 1
	v_add_f32_e32 v54, v16, v54
	v_cvt_f32_i32_e32 v55, s0
	v_add_f32_e32 v54, v17, v54
	v_add_f32_e32 v54, v18, v54
	v_add_f32_e32 v54, v19, v54
	v_div_scale_f32 v56, s[0:1], v55, v55, v54
	v_rcp_f32_e32 v57, v56
; #define POOL_WIN(WIN) do { _Pragma("unroll") for (int t = 0; t < 32; ++t) { float s = 0.f; _Pragma("unroll") for (int j = 0; j < WIN; ++j) s += x[15 + t - j]; \
;             const int pos = pos0 + ts + t; const float cnt = (float)(pos + 1 < WIN ? pos + 1 : WIN); pl[(ts + t) * PS + c] = f2bf(s / cnt - x[15 + t]); } } while (0)
; __device__ __forceinline__ void pool_item(int l, int it, LAS unsigned char* lds, const bf16_t* PLB, bf16_t* YC, const float* pool_w, const float* pool_scale, int tid, int lane, int wave) {
;     ...
;         if (g == 0) POOL_WIN(2); else if (g == 1) POOL_WIN(4); else if (g == 2) POOL_WIN(8); else POOL_WIN(16);
	v_sub_f32_e32 v53, v53, v5
	v_readlane_b32 s0, v254, 4
	v_cvt_pk_bf16_f32 v53, v53, v53
	s_nop 1
	v_add_u32_e32 v58, s0, v43
	ds_write_b16 v58, v53
	v_fma_f32 v53, -v56, v57, 1.0
	v_fmac_f32_e32 v57, v53, v57
	v_div_scale_f32 v53, vcc, v54, v55, v54
	v_mul_f32_e32 v58, v53, v57
	v_fma_f32 v59, -v56, v58, v53
	v_fmac_f32_e32 v58, v59, v57
	v_fma_f32 v53, -v56, v58, v53
	v_div_fmas_f32 v53, v53, v57, v58
	v_div_fixup_f32 v53, v53, v55, v54
	v_add_f32_e32 v54, 0, v1
	v_add_f32_e32 v54, v4, v54
	v_add_f32_e32 v54, v5, v54
	v_add_f32_e32 v54, v6, v54
	v_add_f32_e32 v54, v7, v54
	v_add_f32_e32 v54, v8, v54
	v_add_f32_e32 v54, v9, v54
	v_add_f32_e32 v54, v10, v54
	v_add_f32_e32 v54, v11, v54
	v_add_f32_e32 v54, v12, v54
	s_or_b32 s0, s22, 28
	v_add_f32_e32 v54, v13, v54
	s_min_i32 s0, s0, 15
	v_add_f32_e32 v54, v14, v54
	s_add_i32 s0, s0, 1
	v_add_f32_e32 v54, v15, v54
	v_cvt_f32_i32_e32 v55, s0
	v_add_f32_e32 v54, v16, v54
	v_add_f32_e32 v54, v17, v54
	v_add_f32_e32 v54, v18, v54
	v_div_scale_f32 v56, s[0:1], v55, v55, v54
	v_rcp_f32_e32 v57, v56
	v_sub_f32_e32 v53, v53, v4
	v_readlane_b32 s0, v254, 7
	v_cvt_pk_bf16_f32 v53, v53, v53
	s_nop 1
	v_add_u32_e32 v58, s0, v43
	ds_write_b16 v58, v53
	v_fma_f32 v53, -v56, v57, 1.0
	v_fmac_f32_e32 v57, v53, v57
	v_div_scale_f32 v53, vcc, v54, v55, v54
	v_mul_f32_e32 v58, v53, v57
	v_fma_f32 v59, -v56, v58, v53
	v_fmac_f32_e32 v58, v59, v57
	v_fma_f32 v53, -v56, v58, v53
	v_div_fmas_f32 v53, v53, v57, v58
	v_div_fixup_f32 v53, v53, v55, v54
	v_add_f32_e32 v54, 0, v2
	v_add_f32_e32 v54, v1, v54
	v_add_f32_e32 v54, v4, v54
	v_add_f32_e32 v54, v5, v54
	v_add_f32_e32 v54, v6, v54
	v_add_f32_e32 v54, v7, v54
	v_add_f32_e32 v54, v8, v54
	v_add_f32_e32 v54, v9, v54
	v_add_f32_e32 v54, v10, v54
	v_add_f32_e32 v54, v11, v54
	s_or_b32 s0, s22, 29
	v_add_f32_e32 v54, v12, v54
	s_min_i32 s0, s0, 15
	v_add_f32_e32 v54, v13, v54
	s_add_i32 s0, s0, 1
	v_add_f32_e32 v54, v14, v54
	v_cvt_f32_i32_e32 v55, s0
	v_add_f32_e32 v54, v15, v54
	v_add_f32_e32 v54, v16, v54
	v_add_f32_e32 v54, v17, v54
	v_div_scale_f32 v56, s[0:1], v55, v55, v54
	v_rcp_f32_e32 v57, v56
	v_sub_f32_e32 v53, v53, v1
	v_readlane_b32 s0, v254, 10
	v_cvt_pk_bf16_f32 v53, v53, v53
	s_nop 1
	v_add_u32_e32 v58, s0, v43
	ds_write_b16 v58, v53
	v_fma_f32 v53, -v56, v57, 1.0
	v_fmac_f32_e32 v57, v53, v57
	v_div_scale_f32 v53, vcc, v54, v55, v54
	v_mul_f32_e32 v58, v53, v57
	v_fma_f32 v59, -v56, v58, v53
	v_fmac_f32_e32 v58, v59, v57
	v_fma_f32 v53, -v56, v58, v53
	v_div_fmas_f32 v53, v53, v57, v58
	v_div_fixup_f32 v53, v53, v55, v54
	v_add_f32_e32 v54, 0, v3
	v_add_f32_e32 v54, v2, v54
	v_add_f32_e32 v54, v1, v54
	v_add_f32_e32 v54, v4, v54
	v_add_f32_e32 v54, v5, v54
	v_add_f32_e32 v54, v6, v54
	v_add_f32_e32 v54, v7, v54
	v_add_f32_e32 v54, v8, v54
	v_add_f32_e32 v54, v9, v54
	v_add_f32_e32 v54, v10, v54
	s_or_b32 s0, s22, 30
	v_add_f32_e32 v54, v11, v54
	s_min_i32 s0, s0, 15
	v_add_f32_e32 v54, v12, v54
	s_add_i32 s0, s0, 1
	v_add_f32_e32 v54, v13, v54
	v_cvt_f32_i32_e32 v55, s0
	v_add_f32_e32 v54, v14, v54
	v_add_f32_e32 v54, v15, v54
	v_add_f32_e32 v54, v16, v54
	v_div_scale_f32 v56, s[0:1], v55, v55, v54
	v_rcp_f32_e32 v57, v56
	v_sub_f32_e32 v53, v53, v2
	v_readlane_b32 s0, v254, 13
	v_cvt_pk_bf16_f32 v53, v53, v53
	s_nop 1
	v_add_u32_e32 v58, s0, v43
	ds_write_b16 v58, v53
	v_fma_f32 v53, -v56, v57, 1.0
	v_fmac_f32_e32 v57, v53, v57
	v_div_scale_f32 v53, vcc, v54, v55, v54
	v_mul_f32_e32 v58, v53, v57
	v_fma_f32 v59, -v56, v58, v53
	v_fmac_f32_e32 v58, v59, v57
	v_fma_f32 v53, -v56, v58, v53
	v_div_fmas_f32 v53, v53, v57, v58
	v_div_fixup_f32 v53, v53, v55, v54
	v_add_f32_e32 v54, 0, v0
	v_add_f32_e32 v54, v3, v54
	v_add_f32_e32 v54, v2, v54
	v_add_f32_e32 v54, v1, v54
	v_add_f32_e32 v54, v4, v54
	v_add_f32_e32 v54, v5, v54
	v_add_f32_e32 v54, v6, v54
	v_add_f32_e32 v54, v7, v54
	v_add_f32_e32 v54, v8, v54
	v_add_f32_e32 v54, v9, v54
	s_or_b32 s0, s22, 31
	v_add_f32_e32 v54, v10, v54
	s_min_i32 s0, s0, 15
	v_add_f32_e32 v54, v11, v54
	s_add_i32 s0, s0, 1
	v_add_f32_e32 v54, v12, v54
	v_cvt_f32_i32_e32 v55, s0
	v_add_f32_e32 v54, v13, v54
	v_add_f32_e32 v54, v14, v54
	v_add_f32_e32 v54, v15, v54
	v_div_scale_f32 v56, s[0:1], v55, v55, v54
	v_rcp_f32_e32 v57, v56
	v_sub_f32_e32 v53, v53, v3
	v_readlane_b32 s0, v254, 16
	v_cvt_pk_bf16_f32 v53, v53, v53
	s_nop 1
	v_add_u32_e32 v58, s0, v43
	ds_write_b16 v58, v53
	v_fma_f32 v53, -v56, v57, 1.0
	v_fmac_f32_e32 v57, v53, v57
	v_div_scale_f32 v53, vcc, v54, v55, v54
	v_mul_f32_e32 v58, v53, v57
	v_fma_f32 v59, -v56, v58, v53
	v_fmac_f32_e32 v58, v59, v57
	v_fma_f32 v53, -v56, v58, v53
	v_div_fmas_f32 v53, v53, v57, v58
	v_div_fixup_f32 v53, v53, v55, v54
	v_readlane_b32 s0, v254, 19
	v_sub_f32_e32 v53, v53, v0
	v_cvt_pk_bf16_f32 v53, v53, v53
	s_nop 0
	v_add_u32_e32 v54, s0, v43
	ds_write_b16 v54, v53
